# no s_setprio toggling in the GEMM K-loops (all 16 per iteration removed)
# baseline (speedup 1.0000x reference)
.LBB0_236:
	s_add_i32 s12, s75, 2
	s_add_u32 s30, s28, 0xfff00080
	s_addc_u32 s31, s29, -1
	s_cmp_eq_u32 s72, s75
	s_cselect_b32 s35, s68, s31
	s_cselect_b32 s34, s69, s30
	s_cselect_b32 s31, s70, s74
	s_cselect_b32 s30, s71, s73
	s_cmpk_lt_i32 s3, 0x56
	s_cselect_b32 s36, s58, 0x2b00
	s_mov_b32 s37, 0xac00
	s_cselect_b32 s75, s37, 0x4000
	s_sub_i32 s36, s36, s33
	v_min3_i32 v5, s36, v174, 2
	v_sub_u32_e32 v174, v174, v5
	v_readfirstlane_b32 s78, v5
	s_max_i32 s36, s78, 0
	s_add_i32 s36, s33, s36
	s_add_i32 s76, s36, -1
	s_min_i32 s36, s33, s76
	s_mul_hi_i32 s37, s75, s36
	s_mul_i32 s36, s75, s36
	s_add_u32 s36, s38, s36
	s_addc_u32 s37, s39, s37
	s_mul_hi_i32 s77, s75, s76
	s_mul_i32 s75, s75, s76
	s_add_u32 s76, s38, s75
	global_load_dwordx4 v[152:155], v173, s[36:37] nt
	s_addc_u32 s77, s39, s77
	global_load_dwordx4 v[164:167], v173, s[76:77] nt
	s_add_i32 s33, s78, s33
	ds_read_b128 v[168:171], v160
	ds_read_b128 v[176:179], v160 offset:1024
	ds_read_b128 v[180:183], v160 offset:2048
	ds_read_b128 v[184:187], v160 offset:3072
	ds_read_b128 v[188:191], v160 offset:16384
	ds_read_b128 v[192:195], v160 offset:17408
	ds_read_b128 v[196:199], v160 offset:18432
	ds_read_b128 v[200:203], v160 offset:19456
	s_add_i32 m0, s49, 0xc000
	ds_read_b128 v[204:207], v163
	ds_read_b128 v[208:211], v163 offset:1024
	ds_read_b128 v[212:215], v163 offset:2048
	ds_read_b128 v[216:219], v163 offset:3072
	ds_read_b128 v[220:223], v163 offset:4096
	ds_read_b128 v[224:227], v163 offset:5120
	ds_read_b128 v[228:231], v163 offset:6144
	global_load_lds_dwordx4 v146, s[28:29]
	s_add_i32 m0, s49, 0xe000
	ds_read_b128 v[236:239], v163 offset:7168
	global_load_lds_dwordx4 v148, s[28:29]
	s_waitcnt vmcnt(10) lgkmcnt(0)
	s_barrier
	v_mfma_f32_16x16x32_bf16 v[132:135], v[168:171], v[204:207], v[132:135]
	v_mfma_f32_16x16x32_bf16 v[128:131], v[180:183], v[204:207], v[128:131]
	v_mfma_f32_16x16x32_bf16 v[116:119], v[168:171], v[212:215], v[116:119]
	v_mfma_f32_16x16x32_bf16 v[112:115], v[180:183], v[212:215], v[112:115]
	v_mfma_f32_16x16x32_bf16 v[100:103], v[168:171], v[220:223], v[100:103]
	v_mfma_f32_16x16x32_bf16 v[96:99], v[180:183], v[220:223], v[96:99]
	v_mfma_f32_16x16x32_bf16 v[84:87], v[168:171], v[228:231], v[84:87]
	v_mfma_f32_16x16x32_bf16 v[80:83], v[180:183], v[228:231], v[80:83]
	v_mfma_f32_16x16x32_bf16 v[132:135], v[176:179], v[208:211], v[132:135]
	v_mfma_f32_16x16x32_bf16 v[128:131], v[184:187], v[208:211], v[128:131]
	v_mfma_f32_16x16x32_bf16 v[116:119], v[176:179], v[216:219], v[116:119]
	v_mfma_f32_16x16x32_bf16 v[112:115], v[184:187], v[216:219], v[112:115]
	v_mfma_f32_16x16x32_bf16 v[100:103], v[176:179], v[224:227], v[100:103]
	v_mfma_f32_16x16x32_bf16 v[96:99], v[184:187], v[224:227], v[96:99]
	v_mfma_f32_16x16x32_bf16 v[84:87], v[176:179], v[236:239], v[84:87]
	v_mfma_f32_16x16x32_bf16 v[80:83], v[184:187], v[236:239], v[80:83]
	v_mfma_f32_16x16x32_bf16 v[124:127], v[188:191], v[204:207], v[124:127]
	v_mfma_f32_16x16x32_bf16 v[120:123], v[196:199], v[204:207], v[120:123]
	v_mfma_f32_16x16x32_bf16 v[108:111], v[188:191], v[212:215], v[108:111]
	v_mfma_f32_16x16x32_bf16 v[104:107], v[196:199], v[212:215], v[104:107]
	v_mfma_f32_16x16x32_bf16 v[92:95], v[188:191], v[220:223], v[92:95]
	v_mfma_f32_16x16x32_bf16 v[88:91], v[196:199], v[220:223], v[88:91]
	v_mfma_f32_16x16x32_bf16 v[76:79], v[188:191], v[228:231], v[76:79]
	v_mfma_f32_16x16x32_bf16 v[72:75], v[196:199], v[228:231], v[72:75]
	v_mfma_f32_16x16x32_bf16 v[124:127], v[192:195], v[208:211], v[124:127]
	v_mfma_f32_16x16x32_bf16 v[120:123], v[200:203], v[208:211], v[120:123]
	v_mfma_f32_16x16x32_bf16 v[108:111], v[192:195], v[216:219], v[108:111]
	v_mfma_f32_16x16x32_bf16 v[104:107], v[200:203], v[216:219], v[104:107]
	v_mfma_f32_16x16x32_bf16 v[92:95], v[192:195], v[224:227], v[92:95]
	v_mfma_f32_16x16x32_bf16 v[88:91], v[200:203], v[224:227], v[88:91]
	v_mfma_f32_16x16x32_bf16 v[76:79], v[192:195], v[236:239], v[76:79]
	v_mfma_f32_16x16x32_bf16 v[72:75], v[200:203], v[236:239], v[72:75]
	s_barrier
	s_add_i32 s36, s59, s48
	s_mov_b32 m0, s36
	ds_read_b128 v[204:207], v163 offset:16384
	ds_read_b128 v[208:211], v163 offset:17408
	ds_read_b128 v[212:215], v163 offset:18432
	ds_read_b128 v[216:219], v163 offset:19456
	global_load_lds_dwordx4 v138, s[30:31]
	s_add_i32 m0, s36, 0x2000
	s_add_u32 s36, s30, 0x100000
	s_addc_u32 s37, s31, 0
	s_add_i32 s75, s60, s48
	global_load_lds_dwordx4 v142, s[30:31]
	s_mov_b32 m0, s75
	ds_read_b128 v[236:239], v163 offset:23552
	global_load_lds_dwordx4 v138, s[36:37]
	s_add_i32 m0, s75, 0x2000
	ds_read_b128 v[228:231], v163 offset:22528
	global_load_lds_dwordx4 v142, s[36:37]
	s_mov_b32 m0, s49
	ds_read_b128 v[224:227], v163 offset:21504
	global_load_lds_dwordx4 v136, s[34:35]
	s_mov_b32 m0, s50
	ds_read_b128 v[220:223], v163 offset:20480
	global_load_lds_dwordx4 v140, s[34:35]
	s_waitcnt vmcnt(10) lgkmcnt(0)
	s_barrier
	v_mfma_f32_16x16x32_bf16 v[68:71], v[168:171], v[204:207], v[68:71]
	v_mfma_f32_16x16x32_bf16 v[64:67], v[180:183], v[204:207], v[64:67]
	v_mfma_f32_16x16x32_bf16 v[52:55], v[168:171], v[212:215], v[52:55]
	v_mfma_f32_16x16x32_bf16 v[48:51], v[180:183], v[212:215], v[48:51]
	v_mfma_f32_16x16x32_bf16 v[36:39], v[168:171], v[220:223], v[36:39]
	v_mfma_f32_16x16x32_bf16 v[32:35], v[180:183], v[220:223], v[32:35]
	v_mfma_f32_16x16x32_bf16 v[20:23], v[168:171], v[228:231], v[20:23]
	v_mfma_f32_16x16x32_bf16 v[16:19], v[180:183], v[228:231], v[16:19]
	v_mfma_f32_16x16x32_bf16 v[68:71], v[176:179], v[208:211], v[68:71]
	v_mfma_f32_16x16x32_bf16 v[64:67], v[184:187], v[208:211], v[64:67]
	v_mfma_f32_16x16x32_bf16 v[52:55], v[176:179], v[216:219], v[52:55]
	v_mfma_f32_16x16x32_bf16 v[48:51], v[184:187], v[216:219], v[48:51]
	v_mfma_f32_16x16x32_bf16 v[36:39], v[176:179], v[224:227], v[36:39]
	v_mfma_f32_16x16x32_bf16 v[32:35], v[184:187], v[224:227], v[32:35]
	v_mfma_f32_16x16x32_bf16 v[20:23], v[176:179], v[236:239], v[20:23]
	v_mfma_f32_16x16x32_bf16 v[16:19], v[184:187], v[236:239], v[16:19]
	v_mfma_f32_16x16x32_bf16 v[60:63], v[188:191], v[204:207], v[60:63]
	v_mfma_f32_16x16x32_bf16 v[56:59], v[196:199], v[204:207], v[56:59]
	v_mfma_f32_16x16x32_bf16 v[44:47], v[188:191], v[212:215], v[44:47]
	v_mfma_f32_16x16x32_bf16 v[40:43], v[196:199], v[212:215], v[40:43]
	v_mfma_f32_16x16x32_bf16 v[28:31], v[188:191], v[220:223], v[28:31]
	v_mfma_f32_16x16x32_bf16 v[24:27], v[196:199], v[220:223], v[24:27]
	v_mfma_f32_16x16x32_bf16 v[12:15], v[188:191], v[228:231], v[12:15]
	v_mfma_f32_16x16x32_bf16 v[6:9], v[196:199], v[228:231], v[8:11]
	v_mfma_f32_16x16x32_bf16 v[60:63], v[192:195], v[208:211], v[60:63]
	v_mfma_f32_16x16x32_bf16 v[56:59], v[200:203], v[208:211], v[56:59]
	v_mfma_f32_16x16x32_bf16 v[44:47], v[192:195], v[216:219], v[44:47]
	v_mfma_f32_16x16x32_bf16 v[40:43], v[200:203], v[216:219], v[40:43]
	v_mfma_f32_16x16x32_bf16 v[28:31], v[192:195], v[224:227], v[28:31]
	v_mfma_f32_16x16x32_bf16 v[24:27], v[200:203], v[224:227], v[24:27]
	v_mfma_f32_16x16x32_bf16 v[12:15], v[192:195], v[236:239], v[12:15]
	v_mfma_f32_16x16x32_bf16 v[6:9], v[200:203], v[236:239], v[6:9]
	s_barrier
	s_add_i32 s36, 0, 0x18000
	s_add_i32 s37, 0, 0x1c000
	ds_read_b128 v[168:171], v160 offset:32768
	ds_read_b128 v[176:179], v160 offset:33792
	ds_read_b128 v[180:183], v160 offset:34816
	ds_read_b128 v[184:187], v160 offset:35840
	ds_read_b128 v[188:191], v160 offset:49152
	ds_read_b128 v[192:195], v160 offset:50176
	ds_read_b128 v[196:199], v160 offset:51200
	ds_read_b128 v[200:203], v160 offset:52224
	s_add_u32 s34, s34, 0x100000
	s_addc_u32 s35, s35, 0
	s_mov_b32 m0, s51
	ds_read_b128 v[204:207], v163 offset:32768
	ds_read_b128 v[208:211], v163 offset:33792
	ds_read_b128 v[212:215], v163 offset:34816
	ds_read_b128 v[216:219], v163 offset:35840
	ds_read_b128 v[220:223], v163 offset:36864
	ds_read_b128 v[224:227], v163 offset:37888
	ds_read_b128 v[228:231], v163 offset:38912
	global_load_lds_dwordx4 v136, s[34:35]
	s_mov_b32 m0, s52
	ds_read_b128 v[236:239], v163 offset:39936
	global_load_lds_dwordx4 v140, s[34:35]
	s_waitcnt vmcnt(8) lgkmcnt(0)
	s_barrier
	v_mfma_f32_16x16x32_bf16 v[132:135], v[168:171], v[204:207], v[132:135]
	v_mfma_f32_16x16x32_bf16 v[128:131], v[180:183], v[204:207], v[128:131]
	v_mfma_f32_16x16x32_bf16 v[116:119], v[168:171], v[212:215], v[116:119]
	v_mfma_f32_16x16x32_bf16 v[112:115], v[180:183], v[212:215], v[112:115]
	v_mfma_f32_16x16x32_bf16 v[100:103], v[168:171], v[220:223], v[100:103]
	v_max3_f32 v0, v0, |v152|, |v164|
	v_mfma_f32_16x16x32_bf16 v[96:99], v[180:183], v[220:223], v[96:99]
	v_max3_f32 v1, v1, |v153|, |v165|
	v_mfma_f32_16x16x32_bf16 v[84:87], v[168:171], v[228:231], v[84:87]
	v_max3_f32 v2, v2, |v154|, |v166|
	v_mfma_f32_16x16x32_bf16 v[80:83], v[180:183], v[228:231], v[80:83]
	v_max3_f32 v3, v3, |v155|, |v167|
	v_mfma_f32_16x16x32_bf16 v[132:135], v[176:179], v[208:211], v[132:135]
	v_mfma_f32_16x16x32_bf16 v[128:131], v[184:187], v[208:211], v[128:131]
	v_mfma_f32_16x16x32_bf16 v[116:119], v[176:179], v[216:219], v[116:119]
	v_mfma_f32_16x16x32_bf16 v[112:115], v[184:187], v[216:219], v[112:115]
	v_mfma_f32_16x16x32_bf16 v[100:103], v[176:179], v[224:227], v[100:103]
	v_mfma_f32_16x16x32_bf16 v[96:99], v[184:187], v[224:227], v[96:99]
	v_mfma_f32_16x16x32_bf16 v[84:87], v[176:179], v[236:239], v[84:87]
	v_mfma_f32_16x16x32_bf16 v[80:83], v[184:187], v[236:239], v[80:83]
	v_mfma_f32_16x16x32_bf16 v[124:127], v[188:191], v[204:207], v[124:127]
	v_mfma_f32_16x16x32_bf16 v[120:123], v[196:199], v[204:207], v[120:123]
	v_mfma_f32_16x16x32_bf16 v[108:111], v[188:191], v[212:215], v[108:111]
	v_mfma_f32_16x16x32_bf16 v[104:107], v[196:199], v[212:215], v[104:107]
	v_mfma_f32_16x16x32_bf16 v[92:95], v[188:191], v[220:223], v[92:95]
	v_mfma_f32_16x16x32_bf16 v[88:91], v[196:199], v[220:223], v[88:91]
	v_mfma_f32_16x16x32_bf16 v[76:79], v[188:191], v[228:231], v[76:79]
	v_mfma_f32_16x16x32_bf16 v[72:75], v[196:199], v[228:231], v[72:75]
	v_mfma_f32_16x16x32_bf16 v[124:127], v[192:195], v[208:211], v[124:127]
	v_mfma_f32_16x16x32_bf16 v[120:123], v[200:203], v[208:211], v[120:123]
	v_mfma_f32_16x16x32_bf16 v[108:111], v[192:195], v[216:219], v[108:111]
	v_mfma_f32_16x16x32_bf16 v[104:107], v[200:203], v[216:219], v[104:107]
	v_mfma_f32_16x16x32_bf16 v[92:95], v[192:195], v[224:227], v[92:95]
	v_mfma_f32_16x16x32_bf16 v[88:91], v[200:203], v[224:227], v[88:91]
	v_mfma_f32_16x16x32_bf16 v[76:79], v[192:195], v[236:239], v[76:79]
	v_mfma_f32_16x16x32_bf16 v[72:75], v[200:203], v[236:239], v[72:75]
	s_barrier
	s_add_u32 s98, s30, s10
	s_addc_u32 s99, s31, s11
	s_add_u32 s100, s34, s10
	s_addc_u32 s101, s35, s11
	s_sub_u32 s100, s100, 0x100000
	s_subb_u32 s101, s101, 0
	s_add_i32 s34, s36, s48
	s_mov_b32 m0, s34
	ds_read_b128 v[152:155], v163 offset:49152
	ds_read_b128 v[164:167], v163 offset:50176
	ds_read_b128 v[204:207], v163 offset:51200
	ds_read_b128 v[208:211], v163 offset:52224
	global_load_lds_dwordx4 v138, s[98:99]
	s_add_i32 m0, s34, 0x2000
	s_add_u32 s30, s30, 0x100080
	s_addc_u32 s31, s31, 0
	s_add_i32 s34, s37, s48
	global_load_lds_dwordx4 v142, s[98:99]
	s_mov_b32 m0, s34
	ds_read_b128 v[224:227], v163 offset:56320
	global_load_lds_dwordx4 v138, s[30:31]
	s_add_i32 m0, s34, 0x2000
	ds_read_b128 v[220:223], v163 offset:55296
	global_load_lds_dwordx4 v142, s[30:31]
	s_mov_b32 m0, s56
	ds_read_b128 v[216:219], v163 offset:54272
	global_load_lds_dwordx4 v136, s[100:101]
	s_mov_b32 m0, s57
	ds_read_b128 v[212:215], v163 offset:53248
	global_load_lds_dwordx4 v140, s[100:101]
	s_waitcnt vmcnt(8) lgkmcnt(0)
	s_barrier
	v_mfma_f32_16x16x32_bf16 v[68:71], v[168:171], v[152:155], v[68:71]
	v_mfma_f32_16x16x32_bf16 v[64:67], v[180:183], v[152:155], v[64:67]
	v_mfma_f32_16x16x32_bf16 v[52:55], v[168:171], v[204:207], v[52:55]
	v_mfma_f32_16x16x32_bf16 v[48:51], v[180:183], v[204:207], v[48:51]
	v_mfma_f32_16x16x32_bf16 v[36:39], v[168:171], v[212:215], v[36:39]
	v_mfma_f32_16x16x32_bf16 v[32:35], v[180:183], v[212:215], v[32:35]
	v_mfma_f32_16x16x32_bf16 v[20:23], v[168:171], v[220:223], v[20:23]
	v_mfma_f32_16x16x32_bf16 v[16:19], v[180:183], v[220:223], v[16:19]
	v_mfma_f32_16x16x32_bf16 v[68:71], v[176:179], v[164:167], v[68:71]
	v_mfma_f32_16x16x32_bf16 v[64:67], v[184:187], v[164:167], v[64:67]
	v_mfma_f32_16x16x32_bf16 v[52:55], v[176:179], v[208:211], v[52:55]
	v_mfma_f32_16x16x32_bf16 v[48:51], v[184:187], v[208:211], v[48:51]
	v_mfma_f32_16x16x32_bf16 v[36:39], v[176:179], v[216:219], v[36:39]
	v_mfma_f32_16x16x32_bf16 v[32:35], v[184:187], v[216:219], v[32:35]
	v_mfma_f32_16x16x32_bf16 v[20:23], v[176:179], v[224:227], v[20:23]
	v_mfma_f32_16x16x32_bf16 v[16:19], v[184:187], v[224:227], v[16:19]
	v_mfma_f32_16x16x32_bf16 v[60:63], v[188:191], v[152:155], v[60:63]
	v_mfma_f32_16x16x32_bf16 v[56:59], v[196:199], v[152:155], v[56:59]
	v_mfma_f32_16x16x32_bf16 v[44:47], v[188:191], v[204:207], v[44:47]
	v_mfma_f32_16x16x32_bf16 v[40:43], v[196:199], v[204:207], v[40:43]
	v_mfma_f32_16x16x32_bf16 v[28:31], v[188:191], v[212:215], v[28:31]
	v_mfma_f32_16x16x32_bf16 v[24:27], v[196:199], v[212:215], v[24:27]
	v_mfma_f32_16x16x32_bf16 v[10:13], v[188:191], v[220:223], v[12:15]
	v_mfma_f32_16x16x32_bf16 v[6:9], v[196:199], v[220:223], v[6:9]
	v_mfma_f32_16x16x32_bf16 v[60:63], v[192:195], v[164:167], v[60:63]
	v_mfma_f32_16x16x32_bf16 v[56:59], v[200:203], v[164:167], v[56:59]
	v_mfma_f32_16x16x32_bf16 v[44:47], v[192:195], v[208:211], v[44:47]
	v_mfma_f32_16x16x32_bf16 v[40:43], v[200:203], v[208:211], v[40:43]
	v_mfma_f32_16x16x32_bf16 v[28:31], v[192:195], v[216:219], v[28:31]
	v_mfma_f32_16x16x32_bf16 v[24:27], v[200:203], v[216:219], v[24:27]
	v_mfma_f32_16x16x32_bf16 v[12:15], v[192:195], v[224:227], v[10:13]
	v_mfma_f32_16x16x32_bf16 v[8:11], v[200:203], v[224:227], v[6:9]
	s_barrier
	s_add_u32 s28, s28, 0x100
	s_addc_u32 s29, s29, 0
	s_add_u32 s73, s73, 0x100
	s_addc_u32 s74, s74, 0
	s_cmp_ge_i32 s12, s67
	s_cbranch_scc0 .LBB0_221
	s_and_b64 vcc, exec, s[14:15]
	s_cbranch_vccz .LBB0_239

.Lp1i_body:
	s_add_i32 s8, s74, 2
	s_add_u32 s34, s30, 0xfff80080
	s_addc_u32 s35, s31, -1
	s_cmp_eq_u32 s71, s74
	s_cselect_b32 s37, s67, s35
	s_cselect_b32 s36, s68, s34
	s_cselect_b32 s35, s69, s73
	s_cselect_b32 s34, s70, s72
	ds_read_b128 v[160:163], v177
	ds_read_b128 v[164:167], v177 offset:1024
	ds_read_b128 v[168:171], v177 offset:2048
	ds_read_b128 v[182:185], v177 offset:3072
	ds_read_b128 v[186:189], v177 offset:16384
	ds_read_b128 v[190:193], v177 offset:17408
	ds_read_b128 v[194:197], v177 offset:18432
	ds_read_b128 v[198:201], v177 offset:19456
	s_add_i32 m0, s46, 0xc000
	ds_read_b128 v[202:205], v180
	ds_read_b128 v[206:209], v180 offset:1024
	ds_read_b128 v[210:213], v180 offset:2048
	ds_read_b128 v[214:217], v180 offset:3072
	ds_read_b128 v[218:221], v180 offset:4096
	ds_read_b128 v[222:225], v180 offset:5120
	ds_read_b128 v[226:229], v180 offset:6144
	global_load_lds_dwordx4 v146, s[30:31]
	s_add_i32 m0, s46, 0xe000
	ds_read_b128 v[230:233], v180 offset:7168
	global_load_lds_dwordx4 v148, s[30:31]
	s_waitcnt vmcnt(8) lgkmcnt(0)
	s_barrier
	v_mfma_i32_16x16x64_i8 v[132:135], v[160:163], v[202:205], v[132:135]
	v_mfma_i32_16x16x64_i8 v[128:131], v[168:171], v[202:205], v[128:131]
	v_mfma_i32_16x16x64_i8 v[124:127], v[160:163], v[210:213], v[124:127]
	v_mfma_i32_16x16x64_i8 v[120:123], v[168:171], v[210:213], v[120:123]
	v_mfma_i32_16x16x64_i8 v[112:115], v[160:163], v[218:221], v[112:115]
	v_mfma_i32_16x16x64_i8 v[104:107], v[168:171], v[218:221], v[104:107]
	v_mfma_i32_16x16x64_i8 v[96:99], v[160:163], v[226:229], v[96:99]
	v_mfma_i32_16x16x64_i8 v[88:91], v[168:171], v[226:229], v[88:91]
	v_mfma_i32_16x16x64_i8 v[132:135], v[164:167], v[206:209], v[132:135]
	v_mfma_i32_16x16x64_i8 v[128:131], v[182:185], v[206:209], v[128:131]
	v_mfma_i32_16x16x64_i8 v[124:127], v[164:167], v[214:217], v[124:127]
	v_mfma_i32_16x16x64_i8 v[120:123], v[182:185], v[214:217], v[120:123]
	v_mfma_i32_16x16x64_i8 v[112:115], v[164:167], v[222:225], v[112:115]
	v_mfma_i32_16x16x64_i8 v[104:107], v[182:185], v[222:225], v[104:107]
	v_mfma_i32_16x16x64_i8 v[96:99], v[164:167], v[230:233], v[96:99]
	v_mfma_i32_16x16x64_i8 v[88:91], v[182:185], v[230:233], v[88:91]
	v_mfma_i32_16x16x64_i8 v[116:119], v[186:189], v[202:205], v[116:119]
	v_mfma_i32_16x16x64_i8 v[108:111], v[194:197], v[202:205], v[108:111]
	v_mfma_i32_16x16x64_i8 v[100:103], v[186:189], v[210:213], v[100:103]
	v_mfma_i32_16x16x64_i8 v[92:95], v[194:197], v[210:213], v[92:95]
	v_mfma_i32_16x16x64_i8 v[84:87], v[186:189], v[218:221], v[84:87]
	v_mfma_i32_16x16x64_i8 v[80:83], v[194:197], v[218:221], v[80:83]
	v_mfma_i32_16x16x64_i8 v[76:79], v[186:189], v[226:229], v[76:79]
	v_mfma_i32_16x16x64_i8 v[72:75], v[194:197], v[226:229], v[72:75]
	v_mfma_i32_16x16x64_i8 v[116:119], v[190:193], v[206:209], v[116:119]
	v_mfma_i32_16x16x64_i8 v[108:111], v[198:201], v[206:209], v[108:111]
	v_mfma_i32_16x16x64_i8 v[100:103], v[190:193], v[214:217], v[100:103]
	v_mfma_i32_16x16x64_i8 v[92:95], v[198:201], v[214:217], v[92:95]
	v_mfma_i32_16x16x64_i8 v[84:87], v[190:193], v[222:225], v[84:87]
	v_mfma_i32_16x16x64_i8 v[80:83], v[198:201], v[222:225], v[80:83]
	v_mfma_i32_16x16x64_i8 v[76:79], v[190:193], v[230:233], v[76:79]
	v_mfma_i32_16x16x64_i8 v[72:75], v[198:201], v[230:233], v[72:75]
	s_barrier
	s_add_i32 s74, s57, s45
	s_mov_b32 m0, s74
	ds_read_b128 v[202:205], v180 offset:16384
	ds_read_b128 v[206:209], v180 offset:17408
	ds_read_b128 v[210:213], v180 offset:18432
	ds_read_b128 v[214:217], v180 offset:19456
	global_load_lds_dwordx4 v138, s[34:35]
	s_add_i32 m0, s74, 0x2000
	s_add_u32 s74, s34, 0x80000
	s_addc_u32 s75, s35, 0
	s_add_i32 s76, s58, s45
	global_load_lds_dwordx4 v142, s[34:35]
	s_mov_b32 m0, s76
	ds_read_b128 v[230:233], v180 offset:23552
	global_load_lds_dwordx4 v138, s[74:75]
	s_add_i32 m0, s76, 0x2000
	ds_read_b128 v[226:229], v180 offset:22528
	global_load_lds_dwordx4 v142, s[74:75]
	s_mov_b32 m0, s46
	ds_read_b128 v[222:225], v180 offset:21504
	global_load_lds_dwordx4 v136, s[36:37]
	s_mov_b32 m0, s47
	ds_read_b128 v[218:221], v180 offset:20480
	global_load_lds_dwordx4 v140, s[36:37]
	s_waitcnt vmcnt(8) lgkmcnt(0)
	s_barrier
	v_mfma_i32_16x16x64_i8 v[68:71], v[160:163], v[202:205], v[68:71]
	v_mfma_i32_16x16x64_i8 v[64:67], v[168:171], v[202:205], v[64:67]
	v_mfma_i32_16x16x64_i8 v[60:63], v[160:163], v[210:213], v[60:63]
	v_mfma_i32_16x16x64_i8 v[56:59], v[168:171], v[210:213], v[56:59]
	v_mfma_i32_16x16x64_i8 v[48:51], v[160:163], v[218:221], v[48:51]
	v_mfma_i32_16x16x64_i8 v[40:43], v[168:171], v[218:221], v[40:43]
	v_mfma_i32_16x16x64_i8 v[32:35], v[160:163], v[226:229], v[32:35]
	v_mfma_i32_16x16x64_i8 v[24:27], v[168:171], v[226:229], v[24:27]
	v_mfma_i32_16x16x64_i8 v[68:71], v[164:167], v[206:209], v[68:71]
	v_mfma_i32_16x16x64_i8 v[64:67], v[182:185], v[206:209], v[64:67]
	v_mfma_i32_16x16x64_i8 v[60:63], v[164:167], v[214:217], v[60:63]
	v_mfma_i32_16x16x64_i8 v[56:59], v[182:185], v[214:217], v[56:59]
	v_mfma_i32_16x16x64_i8 v[48:51], v[164:167], v[222:225], v[48:51]
	v_mfma_i32_16x16x64_i8 v[40:43], v[182:185], v[222:225], v[40:43]
	v_mfma_i32_16x16x64_i8 v[32:35], v[164:167], v[230:233], v[32:35]
	v_mfma_i32_16x16x64_i8 v[24:27], v[182:185], v[230:233], v[24:27]
	v_mfma_i32_16x16x64_i8 v[52:55], v[186:189], v[202:205], v[52:55]
	v_mfma_i32_16x16x64_i8 v[44:47], v[194:197], v[202:205], v[44:47]
	v_mfma_i32_16x16x64_i8 v[36:39], v[186:189], v[210:213], v[36:39]
	v_mfma_i32_16x16x64_i8 v[28:31], v[194:197], v[210:213], v[28:31]
	v_mfma_i32_16x16x64_i8 v[20:23], v[186:189], v[218:221], v[20:23]
	v_mfma_i32_16x16x64_i8 v[16:19], v[194:197], v[218:221], v[16:19]
	v_mfma_i32_16x16x64_i8 v[12:15], v[186:189], v[226:229], v[12:15]
	v_mfma_i32_16x16x64_i8 v[6:9], v[194:197], v[226:229], v[8:11]
	v_mfma_i32_16x16x64_i8 v[52:55], v[190:193], v[206:209], v[52:55]
	v_mfma_i32_16x16x64_i8 v[44:47], v[198:201], v[206:209], v[44:47]
	v_mfma_i32_16x16x64_i8 v[36:39], v[190:193], v[214:217], v[36:39]
	v_mfma_i32_16x16x64_i8 v[28:31], v[198:201], v[214:217], v[28:31]
	v_mfma_i32_16x16x64_i8 v[20:23], v[190:193], v[222:225], v[20:23]
	v_mfma_i32_16x16x64_i8 v[16:19], v[198:201], v[222:225], v[16:19]
	v_mfma_i32_16x16x64_i8 v[12:15], v[190:193], v[230:233], v[12:15]
	v_mfma_i32_16x16x64_i8 v[6:9], v[198:201], v[230:233], v[6:9]
	s_barrier
	s_add_i32 s74, 0, 0x18000
	s_add_i32 s75, 0, 0x1c000
	ds_read_b128 v[160:163], v177 offset:32768
	ds_read_b128 v[164:167], v177 offset:33792
	ds_read_b128 v[168:171], v177 offset:34816
	ds_read_b128 v[182:185], v177 offset:35840
	ds_read_b128 v[186:189], v177 offset:49152
	ds_read_b128 v[190:193], v177 offset:50176
	ds_read_b128 v[194:197], v177 offset:51200
	ds_read_b128 v[198:201], v177 offset:52224
	s_add_u32 s36, s36, 0x80000
	s_addc_u32 s37, s37, 0
	s_mov_b32 m0, s48
	ds_read_b128 v[202:205], v180 offset:32768
	ds_read_b128 v[206:209], v180 offset:33792
	ds_read_b128 v[210:213], v180 offset:34816
	ds_read_b128 v[214:217], v180 offset:35840
	ds_read_b128 v[218:221], v180 offset:36864
	ds_read_b128 v[222:225], v180 offset:37888
	ds_read_b128 v[226:229], v180 offset:38912
	global_load_lds_dwordx4 v136, s[36:37]
	s_mov_b32 m0, s49
	ds_read_b128 v[230:233], v180 offset:39936
	global_load_lds_dwordx4 v140, s[36:37]
	s_waitcnt vmcnt(8) lgkmcnt(0)
	s_barrier
	v_mfma_i32_16x16x64_i8 v[132:135], v[160:163], v[202:205], v[132:135]
	v_mfma_i32_16x16x64_i8 v[128:131], v[168:171], v[202:205], v[128:131]
	v_mfma_i32_16x16x64_i8 v[124:127], v[160:163], v[210:213], v[124:127]
	v_mfma_i32_16x16x64_i8 v[120:123], v[168:171], v[210:213], v[120:123]
	v_mfma_i32_16x16x64_i8 v[112:115], v[160:163], v[218:221], v[112:115]
	v_mfma_i32_16x16x64_i8 v[104:107], v[168:171], v[218:221], v[104:107]
	v_mfma_i32_16x16x64_i8 v[96:99], v[160:163], v[226:229], v[96:99]
	v_mfma_i32_16x16x64_i8 v[88:91], v[168:171], v[226:229], v[88:91]
	v_mfma_i32_16x16x64_i8 v[132:135], v[164:167], v[206:209], v[132:135]
	v_mfma_i32_16x16x64_i8 v[128:131], v[182:185], v[206:209], v[128:131]
	v_mfma_i32_16x16x64_i8 v[124:127], v[164:167], v[214:217], v[124:127]
	v_mfma_i32_16x16x64_i8 v[120:123], v[182:185], v[214:217], v[120:123]
	v_mfma_i32_16x16x64_i8 v[112:115], v[164:167], v[222:225], v[112:115]
	v_mfma_i32_16x16x64_i8 v[104:107], v[182:185], v[222:225], v[104:107]
	v_mfma_i32_16x16x64_i8 v[96:99], v[164:167], v[230:233], v[96:99]
	v_mfma_i32_16x16x64_i8 v[88:91], v[182:185], v[230:233], v[88:91]
	v_mfma_i32_16x16x64_i8 v[116:119], v[186:189], v[202:205], v[116:119]
	v_mfma_i32_16x16x64_i8 v[108:111], v[194:197], v[202:205], v[108:111]
	v_mfma_i32_16x16x64_i8 v[100:103], v[186:189], v[210:213], v[100:103]
	v_mfma_i32_16x16x64_i8 v[92:95], v[194:197], v[210:213], v[92:95]
	v_mfma_i32_16x16x64_i8 v[84:87], v[186:189], v[218:221], v[84:87]
	v_mfma_i32_16x16x64_i8 v[80:83], v[194:197], v[218:221], v[80:83]
	v_mfma_i32_16x16x64_i8 v[76:79], v[186:189], v[226:229], v[76:79]
	v_mfma_i32_16x16x64_i8 v[72:75], v[194:197], v[226:229], v[72:75]
	v_mfma_i32_16x16x64_i8 v[116:119], v[190:193], v[206:209], v[116:119]
	v_mfma_i32_16x16x64_i8 v[108:111], v[198:201], v[206:209], v[108:111]
	v_mfma_i32_16x16x64_i8 v[100:103], v[190:193], v[214:217], v[100:103]
	v_mfma_i32_16x16x64_i8 v[92:95], v[198:201], v[214:217], v[92:95]
	v_mfma_i32_16x16x64_i8 v[84:87], v[190:193], v[222:225], v[84:87]
	v_mfma_i32_16x16x64_i8 v[80:83], v[198:201], v[222:225], v[80:83]
	v_mfma_i32_16x16x64_i8 v[76:79], v[190:193], v[230:233], v[76:79]
	v_mfma_i32_16x16x64_i8 v[72:75], v[198:201], v[230:233], v[72:75]
	s_barrier
	s_add_u32 s98, s34, s14
	s_addc_u32 s99, s35, s15
	s_add_u32 s100, s36, s14
	s_addc_u32 s101, s37, s15
	s_sub_u32 s100, s100, 0x80000
	s_subb_u32 s101, s101, 0
	s_add_i32 s36, s74, s45
	s_mov_b32 m0, s36
	ds_read_b128 v[152:155], v180 offset:49152
	ds_read_b128 v[156:159], v180 offset:50176
	ds_read_b128 v[202:205], v180 offset:51200
	ds_read_b128 v[206:209], v180 offset:52224
	global_load_lds_dwordx4 v138, s[98:99]
	s_add_i32 m0, s36, 0x2000
	s_add_u32 s34, s34, 0x80080
	s_addc_u32 s35, s35, 0
	s_add_i32 s36, s75, s45
	global_load_lds_dwordx4 v142, s[98:99]
	s_mov_b32 m0, s36
	ds_read_b128 v[222:225], v180 offset:56320
	global_load_lds_dwordx4 v138, s[34:35]
	s_add_i32 m0, s36, 0x2000
	ds_read_b128 v[218:221], v180 offset:55296
	global_load_lds_dwordx4 v142, s[34:35]
	s_mov_b32 m0, s54
	ds_read_b128 v[214:217], v180 offset:54272
	global_load_lds_dwordx4 v136, s[100:101]
	s_mov_b32 m0, s55
	ds_read_b128 v[210:213], v180 offset:53248
	global_load_lds_dwordx4 v140, s[100:101]
	s_waitcnt vmcnt(8) lgkmcnt(0)
	s_barrier
	v_mfma_i32_16x16x64_i8 v[68:71], v[160:163], v[152:155], v[68:71]
	v_mfma_i32_16x16x64_i8 v[64:67], v[168:171], v[152:155], v[64:67]
	v_mfma_i32_16x16x64_i8 v[60:63], v[160:163], v[202:205], v[60:63]
	v_mfma_i32_16x16x64_i8 v[56:59], v[168:171], v[202:205], v[56:59]
	v_mfma_i32_16x16x64_i8 v[48:51], v[160:163], v[210:213], v[48:51]
	v_mfma_i32_16x16x64_i8 v[40:43], v[168:171], v[210:213], v[40:43]
	v_mfma_i32_16x16x64_i8 v[32:35], v[160:163], v[218:221], v[32:35]
	v_mfma_i32_16x16x64_i8 v[24:27], v[168:171], v[218:221], v[24:27]
	v_mfma_i32_16x16x64_i8 v[68:71], v[164:167], v[156:159], v[68:71]
	v_mfma_i32_16x16x64_i8 v[64:67], v[182:185], v[156:159], v[64:67]
	v_mfma_i32_16x16x64_i8 v[60:63], v[164:167], v[206:209], v[60:63]
	v_mfma_i32_16x16x64_i8 v[56:59], v[182:185], v[206:209], v[56:59]
	v_mfma_i32_16x16x64_i8 v[48:51], v[164:167], v[214:217], v[48:51]
	v_mfma_i32_16x16x64_i8 v[40:43], v[182:185], v[214:217], v[40:43]
	v_mfma_i32_16x16x64_i8 v[32:35], v[164:167], v[222:225], v[32:35]
	v_mfma_i32_16x16x64_i8 v[24:27], v[182:185], v[222:225], v[24:27]
	v_mfma_i32_16x16x64_i8 v[52:55], v[186:189], v[152:155], v[52:55]
	v_mfma_i32_16x16x64_i8 v[44:47], v[194:197], v[152:155], v[44:47]
	v_mfma_i32_16x16x64_i8 v[36:39], v[186:189], v[202:205], v[36:39]
	v_mfma_i32_16x16x64_i8 v[28:31], v[194:197], v[202:205], v[28:31]
	v_mfma_i32_16x16x64_i8 v[20:23], v[186:189], v[210:213], v[20:23]
	v_mfma_i32_16x16x64_i8 v[16:19], v[194:197], v[210:213], v[16:19]
	v_mfma_i32_16x16x64_i8 v[10:13], v[186:189], v[218:221], v[12:15]
	v_mfma_i32_16x16x64_i8 v[6:9], v[194:197], v[218:221], v[6:9]
	v_mfma_i32_16x16x64_i8 v[52:55], v[190:193], v[156:159], v[52:55]
	v_mfma_i32_16x16x64_i8 v[44:47], v[198:201], v[156:159], v[44:47]
	v_mfma_i32_16x16x64_i8 v[36:39], v[190:193], v[206:209], v[36:39]
	v_mfma_i32_16x16x64_i8 v[28:31], v[198:201], v[206:209], v[28:31]
	v_mfma_i32_16x16x64_i8 v[20:23], v[190:193], v[214:217], v[20:23]
	v_mfma_i32_16x16x64_i8 v[16:19], v[198:201], v[214:217], v[16:19]
	v_mfma_i32_16x16x64_i8 v[12:15], v[190:193], v[222:225], v[10:13]
	v_mfma_i32_16x16x64_i8 v[8:11], v[198:201], v[222:225], v[6:9]
	s_barrier
	s_add_u32 s30, s30, 0x100
	s_addc_u32 s31, s31, 0
	s_add_u32 s72, s72, 0x100
	s_addc_u32 s73, s73, 0
	s_cmp_ge_i32 s8, s66
	s_cbranch_scc0 .Lp1i_top
	s_branch .Lp1i_epi

.LBB0_327:
	s_add_i32 s8, s74, 2
	s_add_u32 s34, s30, 0xfff80080
	s_addc_u32 s35, s31, -1
	s_cmp_eq_u32 s71, s74
	s_cselect_b32 s37, s67, s35
	s_cselect_b32 s36, s68, s34
	s_cselect_b32 s35, s69, s73
	s_cselect_b32 s34, s70, s72
	s_cmpk_lt_i32 s3, 0x56
	s_cselect_b32 s74, s56, 0x2b00
	s_mov_b32 s75, 0xac00
	s_cselect_b32 s76, s75, 0x4000
	s_sub_i32 s74, s74, s33
	v_min3_i32 v5, s74, v174, 2
	v_sub_u32_e32 v174, v174, v5
	v_readfirstlane_b32 s78, v5
	s_max_i32 s74, s78, 0
	s_add_i32 s74, s33, s74
	s_add_i32 s77, s74, -1
	s_min_i32 s74, s33, s77
	s_mul_hi_i32 s75, s76, s74
	s_mul_i32 s74, s76, s74
	s_add_u32 s74, s38, s74
	s_addc_u32 s75, s39, s75
	s_mul_hi_i32 s79, s76, s77
	s_mul_i32 s76, s76, s77
	s_add_u32 s76, s38, s76
	global_load_dwordx4 v[152:155], v173, s[74:75] nt
	s_addc_u32 s77, s39, s79
	global_load_dwordx4 v[156:159], v173, s[76:77] nt
	s_add_i32 s33, s78, s33
	ds_read_b128 v[160:163], v177
	ds_read_b128 v[164:167], v177 offset:1024
	ds_read_b128 v[168:171], v177 offset:2048
	ds_read_b128 v[182:185], v177 offset:3072
	ds_read_b128 v[186:189], v177 offset:16384
	ds_read_b128 v[190:193], v177 offset:17408
	ds_read_b128 v[194:197], v177 offset:18432
	ds_read_b128 v[198:201], v177 offset:19456
	s_add_i32 m0, s46, 0xc000
	ds_read_b128 v[202:205], v180
	ds_read_b128 v[206:209], v180 offset:1024
	ds_read_b128 v[210:213], v180 offset:2048
	ds_read_b128 v[214:217], v180 offset:3072
	ds_read_b128 v[218:221], v180 offset:4096
	ds_read_b128 v[222:225], v180 offset:5120
	ds_read_b128 v[226:229], v180 offset:6144
	global_load_lds_dwordx4 v146, s[30:31]
	s_add_i32 m0, s46, 0xe000
	ds_read_b128 v[230:233], v180 offset:7168
	global_load_lds_dwordx4 v148, s[30:31]
	s_waitcnt vmcnt(10) lgkmcnt(0)
	s_barrier
	v_mfma_i32_16x16x64_i8 v[132:135], v[160:163], v[202:205], v[132:135]
	v_mfma_i32_16x16x64_i8 v[128:131], v[168:171], v[202:205], v[128:131]
	v_mfma_i32_16x16x64_i8 v[124:127], v[160:163], v[210:213], v[124:127]
	v_mfma_i32_16x16x64_i8 v[120:123], v[168:171], v[210:213], v[120:123]
	v_mfma_i32_16x16x64_i8 v[112:115], v[160:163], v[218:221], v[112:115]
	v_mfma_i32_16x16x64_i8 v[104:107], v[168:171], v[218:221], v[104:107]
	v_mfma_i32_16x16x64_i8 v[96:99], v[160:163], v[226:229], v[96:99]
	v_mfma_i32_16x16x64_i8 v[88:91], v[168:171], v[226:229], v[88:91]
	v_mfma_i32_16x16x64_i8 v[132:135], v[164:167], v[206:209], v[132:135]
	v_mfma_i32_16x16x64_i8 v[128:131], v[182:185], v[206:209], v[128:131]
	v_mfma_i32_16x16x64_i8 v[124:127], v[164:167], v[214:217], v[124:127]
	v_mfma_i32_16x16x64_i8 v[120:123], v[182:185], v[214:217], v[120:123]
	v_mfma_i32_16x16x64_i8 v[112:115], v[164:167], v[222:225], v[112:115]
	v_mfma_i32_16x16x64_i8 v[104:107], v[182:185], v[222:225], v[104:107]
	v_mfma_i32_16x16x64_i8 v[96:99], v[164:167], v[230:233], v[96:99]
	v_mfma_i32_16x16x64_i8 v[88:91], v[182:185], v[230:233], v[88:91]
	v_mfma_i32_16x16x64_i8 v[116:119], v[186:189], v[202:205], v[116:119]
	v_mfma_i32_16x16x64_i8 v[108:111], v[194:197], v[202:205], v[108:111]
	v_mfma_i32_16x16x64_i8 v[100:103], v[186:189], v[210:213], v[100:103]
	v_mfma_i32_16x16x64_i8 v[92:95], v[194:197], v[210:213], v[92:95]
	v_mfma_i32_16x16x64_i8 v[84:87], v[186:189], v[218:221], v[84:87]
	v_mfma_i32_16x16x64_i8 v[80:83], v[194:197], v[218:221], v[80:83]
	v_mfma_i32_16x16x64_i8 v[76:79], v[186:189], v[226:229], v[76:79]
	v_mfma_i32_16x16x64_i8 v[72:75], v[194:197], v[226:229], v[72:75]
	v_mfma_i32_16x16x64_i8 v[116:119], v[190:193], v[206:209], v[116:119]
	v_mfma_i32_16x16x64_i8 v[108:111], v[198:201], v[206:209], v[108:111]
	v_mfma_i32_16x16x64_i8 v[100:103], v[190:193], v[214:217], v[100:103]
	v_mfma_i32_16x16x64_i8 v[92:95], v[198:201], v[214:217], v[92:95]
	v_mfma_i32_16x16x64_i8 v[84:87], v[190:193], v[222:225], v[84:87]
	v_mfma_i32_16x16x64_i8 v[80:83], v[198:201], v[222:225], v[80:83]
	v_mfma_i32_16x16x64_i8 v[76:79], v[190:193], v[230:233], v[76:79]
	v_mfma_i32_16x16x64_i8 v[72:75], v[198:201], v[230:233], v[72:75]
	s_barrier
	s_add_i32 s74, s57, s45
	s_mov_b32 m0, s74
	ds_read_b128 v[202:205], v180 offset:16384
	ds_read_b128 v[206:209], v180 offset:17408
	ds_read_b128 v[210:213], v180 offset:18432
	ds_read_b128 v[214:217], v180 offset:19456
	global_load_lds_dwordx4 v138, s[34:35]
	s_add_i32 m0, s74, 0x2000
	s_add_u32 s74, s34, 0x80000
	s_addc_u32 s75, s35, 0
	s_add_i32 s76, s58, s45
	global_load_lds_dwordx4 v142, s[34:35]
	s_mov_b32 m0, s76
	ds_read_b128 v[230:233], v180 offset:23552
	global_load_lds_dwordx4 v138, s[74:75]
	s_add_i32 m0, s76, 0x2000
	ds_read_b128 v[226:229], v180 offset:22528
	global_load_lds_dwordx4 v142, s[74:75]
	s_mov_b32 m0, s46
	ds_read_b128 v[222:225], v180 offset:21504
	global_load_lds_dwordx4 v136, s[36:37]
	s_mov_b32 m0, s47
	ds_read_b128 v[218:221], v180 offset:20480
	global_load_lds_dwordx4 v140, s[36:37]
	s_waitcnt vmcnt(10) lgkmcnt(0)
	s_barrier
	v_mfma_i32_16x16x64_i8 v[68:71], v[160:163], v[202:205], v[68:71]
	v_mfma_i32_16x16x64_i8 v[64:67], v[168:171], v[202:205], v[64:67]
	v_mfma_i32_16x16x64_i8 v[60:63], v[160:163], v[210:213], v[60:63]
	v_mfma_i32_16x16x64_i8 v[56:59], v[168:171], v[210:213], v[56:59]
	v_mfma_i32_16x16x64_i8 v[48:51], v[160:163], v[218:221], v[48:51]
	v_mfma_i32_16x16x64_i8 v[40:43], v[168:171], v[218:221], v[40:43]
	v_mfma_i32_16x16x64_i8 v[32:35], v[160:163], v[226:229], v[32:35]
	v_mfma_i32_16x16x64_i8 v[24:27], v[168:171], v[226:229], v[24:27]
	v_mfma_i32_16x16x64_i8 v[68:71], v[164:167], v[206:209], v[68:71]
	v_mfma_i32_16x16x64_i8 v[64:67], v[182:185], v[206:209], v[64:67]
	v_mfma_i32_16x16x64_i8 v[60:63], v[164:167], v[214:217], v[60:63]
	v_mfma_i32_16x16x64_i8 v[56:59], v[182:185], v[214:217], v[56:59]
	v_mfma_i32_16x16x64_i8 v[48:51], v[164:167], v[222:225], v[48:51]
	v_mfma_i32_16x16x64_i8 v[40:43], v[182:185], v[222:225], v[40:43]
	v_mfma_i32_16x16x64_i8 v[32:35], v[164:167], v[230:233], v[32:35]
	v_mfma_i32_16x16x64_i8 v[24:27], v[182:185], v[230:233], v[24:27]
	v_mfma_i32_16x16x64_i8 v[52:55], v[186:189], v[202:205], v[52:55]
	v_mfma_i32_16x16x64_i8 v[44:47], v[194:197], v[202:205], v[44:47]
	v_mfma_i32_16x16x64_i8 v[36:39], v[186:189], v[210:213], v[36:39]
	v_mfma_i32_16x16x64_i8 v[28:31], v[194:197], v[210:213], v[28:31]
	v_mfma_i32_16x16x64_i8 v[20:23], v[186:189], v[218:221], v[20:23]
	v_mfma_i32_16x16x64_i8 v[16:19], v[194:197], v[218:221], v[16:19]
	v_mfma_i32_16x16x64_i8 v[12:15], v[186:189], v[226:229], v[12:15]
	v_mfma_i32_16x16x64_i8 v[6:9], v[194:197], v[226:229], v[8:11]
	v_mfma_i32_16x16x64_i8 v[52:55], v[190:193], v[206:209], v[52:55]
	v_mfma_i32_16x16x64_i8 v[44:47], v[198:201], v[206:209], v[44:47]
	v_mfma_i32_16x16x64_i8 v[36:39], v[190:193], v[214:217], v[36:39]
	v_mfma_i32_16x16x64_i8 v[28:31], v[198:201], v[214:217], v[28:31]
	v_mfma_i32_16x16x64_i8 v[20:23], v[190:193], v[222:225], v[20:23]
	v_mfma_i32_16x16x64_i8 v[16:19], v[198:201], v[222:225], v[16:19]
	v_mfma_i32_16x16x64_i8 v[12:15], v[190:193], v[230:233], v[12:15]
	v_mfma_i32_16x16x64_i8 v[6:9], v[198:201], v[230:233], v[6:9]
	s_barrier
	s_add_i32 s74, 0, 0x18000
	s_add_i32 s75, 0, 0x1c000
	ds_read_b128 v[160:163], v177 offset:32768
	ds_read_b128 v[164:167], v177 offset:33792
	ds_read_b128 v[168:171], v177 offset:34816
	ds_read_b128 v[182:185], v177 offset:35840
	ds_read_b128 v[186:189], v177 offset:49152
	ds_read_b128 v[190:193], v177 offset:50176
	ds_read_b128 v[194:197], v177 offset:51200
	ds_read_b128 v[198:201], v177 offset:52224
	s_add_u32 s36, s36, 0x80000
	s_addc_u32 s37, s37, 0
	s_mov_b32 m0, s48
	ds_read_b128 v[202:205], v180 offset:32768
	ds_read_b128 v[206:209], v180 offset:33792
	ds_read_b128 v[210:213], v180 offset:34816
	ds_read_b128 v[214:217], v180 offset:35840
	ds_read_b128 v[218:221], v180 offset:36864
	ds_read_b128 v[222:225], v180 offset:37888
	ds_read_b128 v[226:229], v180 offset:38912
	global_load_lds_dwordx4 v136, s[36:37]
	s_mov_b32 m0, s49
	ds_read_b128 v[230:233], v180 offset:39936
	global_load_lds_dwordx4 v140, s[36:37]
	s_waitcnt vmcnt(8) lgkmcnt(0)
	s_barrier
	v_mfma_i32_16x16x64_i8 v[132:135], v[160:163], v[202:205], v[132:135]
	v_mfma_i32_16x16x64_i8 v[128:131], v[168:171], v[202:205], v[128:131]
	v_mfma_i32_16x16x64_i8 v[124:127], v[160:163], v[210:213], v[124:127]
	v_mfma_i32_16x16x64_i8 v[120:123], v[168:171], v[210:213], v[120:123]
	v_mfma_i32_16x16x64_i8 v[112:115], v[160:163], v[218:221], v[112:115]
	v_max3_f32 v0, v0, |v152|, |v156|
	v_mfma_i32_16x16x64_i8 v[104:107], v[168:171], v[218:221], v[104:107]
	v_max3_f32 v1, v1, |v153|, |v157|
	v_mfma_i32_16x16x64_i8 v[96:99], v[160:163], v[226:229], v[96:99]
	v_max3_f32 v2, v2, |v154|, |v158|
	v_mfma_i32_16x16x64_i8 v[88:91], v[168:171], v[226:229], v[88:91]
	v_max3_f32 v3, v3, |v155|, |v159|
	v_mfma_i32_16x16x64_i8 v[132:135], v[164:167], v[206:209], v[132:135]
	v_mfma_i32_16x16x64_i8 v[128:131], v[182:185], v[206:209], v[128:131]
	v_mfma_i32_16x16x64_i8 v[124:127], v[164:167], v[214:217], v[124:127]
	v_mfma_i32_16x16x64_i8 v[120:123], v[182:185], v[214:217], v[120:123]
	v_mfma_i32_16x16x64_i8 v[112:115], v[164:167], v[222:225], v[112:115]
	v_mfma_i32_16x16x64_i8 v[104:107], v[182:185], v[222:225], v[104:107]
	v_mfma_i32_16x16x64_i8 v[96:99], v[164:167], v[230:233], v[96:99]
	v_mfma_i32_16x16x64_i8 v[88:91], v[182:185], v[230:233], v[88:91]
	v_mfma_i32_16x16x64_i8 v[116:119], v[186:189], v[202:205], v[116:119]
	v_mfma_i32_16x16x64_i8 v[108:111], v[194:197], v[202:205], v[108:111]
	v_mfma_i32_16x16x64_i8 v[100:103], v[186:189], v[210:213], v[100:103]
	v_mfma_i32_16x16x64_i8 v[92:95], v[194:197], v[210:213], v[92:95]
	v_mfma_i32_16x16x64_i8 v[84:87], v[186:189], v[218:221], v[84:87]
	v_mfma_i32_16x16x64_i8 v[80:83], v[194:197], v[218:221], v[80:83]
	v_mfma_i32_16x16x64_i8 v[76:79], v[186:189], v[226:229], v[76:79]
	v_mfma_i32_16x16x64_i8 v[72:75], v[194:197], v[226:229], v[72:75]
	v_mfma_i32_16x16x64_i8 v[116:119], v[190:193], v[206:209], v[116:119]
	v_mfma_i32_16x16x64_i8 v[108:111], v[198:201], v[206:209], v[108:111]
	v_mfma_i32_16x16x64_i8 v[100:103], v[190:193], v[214:217], v[100:103]
	v_mfma_i32_16x16x64_i8 v[92:95], v[198:201], v[214:217], v[92:95]
	v_mfma_i32_16x16x64_i8 v[84:87], v[190:193], v[222:225], v[84:87]
	v_mfma_i32_16x16x64_i8 v[80:83], v[198:201], v[222:225], v[80:83]
	v_mfma_i32_16x16x64_i8 v[76:79], v[190:193], v[230:233], v[76:79]
	v_mfma_i32_16x16x64_i8 v[72:75], v[198:201], v[230:233], v[72:75]
	s_barrier
	s_add_u32 s98, s34, s14
	s_addc_u32 s99, s35, s15
	s_add_u32 s100, s36, s14
	s_addc_u32 s101, s37, s15
	s_sub_u32 s100, s100, 0x80000
	s_subb_u32 s101, s101, 0
	s_add_i32 s36, s74, s45
	s_mov_b32 m0, s36
	ds_read_b128 v[152:155], v180 offset:49152
	ds_read_b128 v[156:159], v180 offset:50176
	ds_read_b128 v[202:205], v180 offset:51200
	ds_read_b128 v[206:209], v180 offset:52224
	global_load_lds_dwordx4 v138, s[98:99]
	s_add_i32 m0, s36, 0x2000
	s_add_u32 s34, s34, 0x80080
	s_addc_u32 s35, s35, 0
	s_add_i32 s36, s75, s45
	global_load_lds_dwordx4 v142, s[98:99]
	s_mov_b32 m0, s36
	ds_read_b128 v[222:225], v180 offset:56320
	global_load_lds_dwordx4 v138, s[34:35]
	s_add_i32 m0, s36, 0x2000
	ds_read_b128 v[218:221], v180 offset:55296
	global_load_lds_dwordx4 v142, s[34:35]
	s_mov_b32 m0, s54
	ds_read_b128 v[214:217], v180 offset:54272
	global_load_lds_dwordx4 v136, s[100:101]
	s_mov_b32 m0, s55
	ds_read_b128 v[210:213], v180 offset:53248
	global_load_lds_dwordx4 v140, s[100:101]
	s_waitcnt vmcnt(8) lgkmcnt(0)
	s_barrier
	v_mfma_i32_16x16x64_i8 v[68:71], v[160:163], v[152:155], v[68:71]
	v_mfma_i32_16x16x64_i8 v[64:67], v[168:171], v[152:155], v[64:67]
	v_mfma_i32_16x16x64_i8 v[60:63], v[160:163], v[202:205], v[60:63]
	v_mfma_i32_16x16x64_i8 v[56:59], v[168:171], v[202:205], v[56:59]
	v_mfma_i32_16x16x64_i8 v[48:51], v[160:163], v[210:213], v[48:51]
	v_mfma_i32_16x16x64_i8 v[40:43], v[168:171], v[210:213], v[40:43]
	v_mfma_i32_16x16x64_i8 v[32:35], v[160:163], v[218:221], v[32:35]
	v_mfma_i32_16x16x64_i8 v[24:27], v[168:171], v[218:221], v[24:27]
	v_mfma_i32_16x16x64_i8 v[68:71], v[164:167], v[156:159], v[68:71]
	v_mfma_i32_16x16x64_i8 v[64:67], v[182:185], v[156:159], v[64:67]
	v_mfma_i32_16x16x64_i8 v[60:63], v[164:167], v[206:209], v[60:63]
	v_mfma_i32_16x16x64_i8 v[56:59], v[182:185], v[206:209], v[56:59]
	v_mfma_i32_16x16x64_i8 v[48:51], v[164:167], v[214:217], v[48:51]
	v_mfma_i32_16x16x64_i8 v[40:43], v[182:185], v[214:217], v[40:43]
	v_mfma_i32_16x16x64_i8 v[32:35], v[164:167], v[222:225], v[32:35]
	v_mfma_i32_16x16x64_i8 v[24:27], v[182:185], v[222:225], v[24:27]
	v_mfma_i32_16x16x64_i8 v[52:55], v[186:189], v[152:155], v[52:55]
	v_mfma_i32_16x16x64_i8 v[44:47], v[194:197], v[152:155], v[44:47]
	v_mfma_i32_16x16x64_i8 v[36:39], v[186:189], v[202:205], v[36:39]
	v_mfma_i32_16x16x64_i8 v[28:31], v[194:197], v[202:205], v[28:31]
	v_mfma_i32_16x16x64_i8 v[20:23], v[186:189], v[210:213], v[20:23]
	v_mfma_i32_16x16x64_i8 v[16:19], v[194:197], v[210:213], v[16:19]
	v_mfma_i32_16x16x64_i8 v[10:13], v[186:189], v[218:221], v[12:15]
	v_mfma_i32_16x16x64_i8 v[6:9], v[194:197], v[218:221], v[6:9]
	v_mfma_i32_16x16x64_i8 v[52:55], v[190:193], v[156:159], v[52:55]
	v_mfma_i32_16x16x64_i8 v[44:47], v[198:201], v[156:159], v[44:47]
	v_mfma_i32_16x16x64_i8 v[36:39], v[190:193], v[206:209], v[36:39]
	v_mfma_i32_16x16x64_i8 v[28:31], v[198:201], v[206:209], v[28:31]
	v_mfma_i32_16x16x64_i8 v[20:23], v[190:193], v[214:217], v[20:23]
	v_mfma_i32_16x16x64_i8 v[16:19], v[198:201], v[214:217], v[16:19]
	v_mfma_i32_16x16x64_i8 v[12:15], v[190:193], v[222:225], v[10:13]
	v_mfma_i32_16x16x64_i8 v[8:11], v[198:201], v[222:225], v[6:9]
	s_barrier
	s_add_u32 s30, s30, 0x100
	s_addc_u32 s31, s31, 0
	s_add_u32 s72, s72, 0x100
	s_addc_u32 s73, s73, 0
	s_cmp_ge_i32 s8, s66
	s_cbranch_scc0 .LBB0_312

.Lp4_body:
	s_add_i32 s8, s71, 2
	s_add_u32 s28, s26, 0xfff00080
	s_addc_u32 s29, s27, -1
	s_cmp_eq_u32 s68, s71
	s_cselect_b32 s31, s64, s29
	s_cselect_b32 s30, s65, s28
	s_cselect_b32 s29, s66, s70
	s_cselect_b32 s28, s67, s69
	ds_read_b128 v[172:175], v163
	ds_read_b128 v[176:179], v163 offset:1024
	ds_read_b128 v[180:183], v163 offset:2048
	ds_read_b128 v[184:187], v163 offset:3072
	ds_read_b128 v[188:191], v163 offset:16384
	ds_read_b128 v[192:195], v163 offset:17408
	ds_read_b128 v[196:199], v163 offset:18432
	ds_read_b128 v[200:203], v163 offset:19456
	s_add_i32 m0, s43, 0xc000
	ds_read_b128 v[204:207], v166
	ds_read_b128 v[208:211], v166 offset:1024
	ds_read_b128 v[212:215], v166 offset:2048
	ds_read_b128 v[216:219], v166 offset:3072
	ds_read_b128 v[220:223], v166 offset:4096
	ds_read_b128 v[224:227], v166 offset:5120
	ds_read_b128 v[236:239], v166 offset:6144
	global_load_lds_dwordx4 v146, s[26:27]
	s_add_i32 m0, s43, 0xe000
	ds_read_b128 v[240:243], v166 offset:7168
	global_load_lds_dwordx4 v148, s[26:27]
	s_waitcnt vmcnt(8) lgkmcnt(0)
	s_barrier
	v_mfma_f32_16x16x32_bf16 v[132:135], v[172:175], v[204:207], v[132:135]
	v_mfma_f32_16x16x32_bf16 v[128:131], v[180:183], v[204:207], v[128:131]
	v_mfma_f32_16x16x32_bf16 v[116:119], v[172:175], v[212:215], v[116:119]
	v_mfma_f32_16x16x32_bf16 v[112:115], v[180:183], v[212:215], v[112:115]
	v_mfma_f32_16x16x32_bf16 v[100:103], v[172:175], v[220:223], v[100:103]
	v_mfma_f32_16x16x32_bf16 v[96:99], v[180:183], v[220:223], v[96:99]
	v_mfma_f32_16x16x32_bf16 v[84:87], v[172:175], v[236:239], v[84:87]
	v_mfma_f32_16x16x32_bf16 v[80:83], v[180:183], v[236:239], v[80:83]
	v_mfma_f32_16x16x32_bf16 v[132:135], v[176:179], v[208:211], v[132:135]
	v_mfma_f32_16x16x32_bf16 v[128:131], v[184:187], v[208:211], v[128:131]
	v_mfma_f32_16x16x32_bf16 v[116:119], v[176:179], v[216:219], v[116:119]
	v_mfma_f32_16x16x32_bf16 v[112:115], v[184:187], v[216:219], v[112:115]
	v_mfma_f32_16x16x32_bf16 v[100:103], v[176:179], v[224:227], v[100:103]
	v_mfma_f32_16x16x32_bf16 v[96:99], v[184:187], v[224:227], v[96:99]
	v_mfma_f32_16x16x32_bf16 v[84:87], v[176:179], v[240:243], v[84:87]
	v_mfma_f32_16x16x32_bf16 v[80:83], v[184:187], v[240:243], v[80:83]
	v_mfma_f32_16x16x32_bf16 v[124:127], v[188:191], v[204:207], v[124:127]
	v_mfma_f32_16x16x32_bf16 v[120:123], v[196:199], v[204:207], v[120:123]
	v_mfma_f32_16x16x32_bf16 v[108:111], v[188:191], v[212:215], v[108:111]
	v_mfma_f32_16x16x32_bf16 v[104:107], v[196:199], v[212:215], v[104:107]
	v_mfma_f32_16x16x32_bf16 v[92:95], v[188:191], v[220:223], v[92:95]
	v_mfma_f32_16x16x32_bf16 v[88:91], v[196:199], v[220:223], v[88:91]
	v_mfma_f32_16x16x32_bf16 v[76:79], v[188:191], v[236:239], v[76:79]
	v_mfma_f32_16x16x32_bf16 v[72:75], v[196:199], v[236:239], v[72:75]
	v_mfma_f32_16x16x32_bf16 v[124:127], v[192:195], v[208:211], v[124:127]
	v_mfma_f32_16x16x32_bf16 v[120:123], v[200:203], v[208:211], v[120:123]
	v_mfma_f32_16x16x32_bf16 v[108:111], v[192:195], v[216:219], v[108:111]
	v_mfma_f32_16x16x32_bf16 v[104:107], v[200:203], v[216:219], v[104:107]
	v_mfma_f32_16x16x32_bf16 v[92:95], v[192:195], v[224:227], v[92:95]
	v_mfma_f32_16x16x32_bf16 v[88:91], v[200:203], v[224:227], v[88:91]
	v_mfma_f32_16x16x32_bf16 v[76:79], v[192:195], v[240:243], v[76:79]
	v_mfma_f32_16x16x32_bf16 v[72:75], v[200:203], v[240:243], v[72:75]
	s_barrier
	s_add_i32 s71, s53, s40
	s_mov_b32 m0, s71
	ds_read_b128 v[204:207], v166 offset:16384
	ds_read_b128 v[208:211], v166 offset:17408
	ds_read_b128 v[212:215], v166 offset:18432
	ds_read_b128 v[216:219], v166 offset:19456
	global_load_lds_dwordx4 v138, s[28:29]
	s_add_i32 m0, s71, 0x2000
	s_add_u32 s72, s28, 0x100000
	s_addc_u32 s73, s29, 0
	s_add_i32 s71, s54, s40
	global_load_lds_dwordx4 v142, s[28:29]
	s_mov_b32 m0, s71
	ds_read_b128 v[240:243], v166 offset:23552
	global_load_lds_dwordx4 v138, s[72:73]
	s_add_i32 m0, s71, 0x2000
	ds_read_b128 v[236:239], v166 offset:22528
	global_load_lds_dwordx4 v142, s[72:73]
	s_mov_b32 m0, s43
	ds_read_b128 v[224:227], v166 offset:21504
	global_load_lds_dwordx4 v136, s[30:31]
	s_mov_b32 m0, s44
	ds_read_b128 v[220:223], v166 offset:20480
	global_load_lds_dwordx4 v140, s[30:31]
	s_waitcnt vmcnt(8) lgkmcnt(0)
	s_barrier
	v_mfma_f32_16x16x32_bf16 v[68:71], v[172:175], v[204:207], v[68:71]
	v_mfma_f32_16x16x32_bf16 v[64:67], v[180:183], v[204:207], v[64:67]
	v_mfma_f32_16x16x32_bf16 v[52:55], v[172:175], v[212:215], v[52:55]
	v_mfma_f32_16x16x32_bf16 v[48:51], v[180:183], v[212:215], v[48:51]
	v_mfma_f32_16x16x32_bf16 v[36:39], v[172:175], v[220:223], v[36:39]
	v_mfma_f32_16x16x32_bf16 v[32:35], v[180:183], v[220:223], v[32:35]
	v_mfma_f32_16x16x32_bf16 v[20:23], v[172:175], v[236:239], v[20:23]
	v_mfma_f32_16x16x32_bf16 v[16:19], v[180:183], v[236:239], v[16:19]
	v_mfma_f32_16x16x32_bf16 v[68:71], v[176:179], v[208:211], v[68:71]
	v_mfma_f32_16x16x32_bf16 v[64:67], v[184:187], v[208:211], v[64:67]
	v_mfma_f32_16x16x32_bf16 v[52:55], v[176:179], v[216:219], v[52:55]
	v_mfma_f32_16x16x32_bf16 v[48:51], v[184:187], v[216:219], v[48:51]
	v_mfma_f32_16x16x32_bf16 v[36:39], v[176:179], v[224:227], v[36:39]
	v_mfma_f32_16x16x32_bf16 v[32:35], v[184:187], v[224:227], v[32:35]
	v_mfma_f32_16x16x32_bf16 v[20:23], v[176:179], v[240:243], v[20:23]
	v_mfma_f32_16x16x32_bf16 v[16:19], v[184:187], v[240:243], v[16:19]
	v_mfma_f32_16x16x32_bf16 v[60:63], v[188:191], v[204:207], v[60:63]
	v_mfma_f32_16x16x32_bf16 v[56:59], v[196:199], v[204:207], v[56:59]
	v_mfma_f32_16x16x32_bf16 v[44:47], v[188:191], v[212:215], v[44:47]
	v_mfma_f32_16x16x32_bf16 v[40:43], v[196:199], v[212:215], v[40:43]
	v_mfma_f32_16x16x32_bf16 v[28:31], v[188:191], v[220:223], v[28:31]
	v_mfma_f32_16x16x32_bf16 v[24:27], v[196:199], v[220:223], v[24:27]
	v_mfma_f32_16x16x32_bf16 v[12:15], v[188:191], v[236:239], v[12:15]
	v_mfma_f32_16x16x32_bf16 v[6:9], v[196:199], v[236:239], v[8:11]
	v_mfma_f32_16x16x32_bf16 v[60:63], v[192:195], v[208:211], v[60:63]
	v_mfma_f32_16x16x32_bf16 v[56:59], v[200:203], v[208:211], v[56:59]
	v_mfma_f32_16x16x32_bf16 v[44:47], v[192:195], v[216:219], v[44:47]
	v_mfma_f32_16x16x32_bf16 v[40:43], v[200:203], v[216:219], v[40:43]
	v_mfma_f32_16x16x32_bf16 v[28:31], v[192:195], v[224:227], v[28:31]
	v_mfma_f32_16x16x32_bf16 v[24:27], v[200:203], v[224:227], v[24:27]
	v_mfma_f32_16x16x32_bf16 v[12:15], v[192:195], v[240:243], v[12:15]
	v_mfma_f32_16x16x32_bf16 v[6:9], v[200:203], v[240:243], v[6:9]
	s_barrier
	s_add_i32 s71, 0, 0x18000
	s_add_i32 s72, 0, 0x1c000
	ds_read_b128 v[172:175], v163 offset:32768
	ds_read_b128 v[176:179], v163 offset:33792
	ds_read_b128 v[180:183], v163 offset:34816
	ds_read_b128 v[184:187], v163 offset:35840
	ds_read_b128 v[188:191], v163 offset:49152
	ds_read_b128 v[192:195], v163 offset:50176
	ds_read_b128 v[196:199], v163 offset:51200
	ds_read_b128 v[200:203], v163 offset:52224
	s_add_u32 s30, s30, 0x100000
	s_addc_u32 s31, s31, 0
	s_mov_b32 m0, s45
	ds_read_b128 v[204:207], v166 offset:32768
	ds_read_b128 v[208:211], v166 offset:33792
	ds_read_b128 v[212:215], v166 offset:34816
	ds_read_b128 v[216:219], v166 offset:35840
	ds_read_b128 v[220:223], v166 offset:36864
	ds_read_b128 v[224:227], v166 offset:37888
	ds_read_b128 v[236:239], v166 offset:38912
	global_load_lds_dwordx4 v136, s[30:31]
	s_mov_b32 m0, s46
	ds_read_b128 v[240:243], v166 offset:39936
	global_load_lds_dwordx4 v140, s[30:31]
	s_waitcnt vmcnt(8) lgkmcnt(0)
	s_barrier
	v_mfma_f32_16x16x32_bf16 v[132:135], v[172:175], v[204:207], v[132:135]
	v_mfma_f32_16x16x32_bf16 v[128:131], v[180:183], v[204:207], v[128:131]
	v_mfma_f32_16x16x32_bf16 v[116:119], v[172:175], v[212:215], v[116:119]
	v_mfma_f32_16x16x32_bf16 v[112:115], v[180:183], v[212:215], v[112:115]
	v_mfma_f32_16x16x32_bf16 v[100:103], v[172:175], v[220:223], v[100:103]
	v_mfma_f32_16x16x32_bf16 v[96:99], v[180:183], v[220:223], v[96:99]
	v_mfma_f32_16x16x32_bf16 v[84:87], v[172:175], v[236:239], v[84:87]
	v_mfma_f32_16x16x32_bf16 v[80:83], v[180:183], v[236:239], v[80:83]
	v_mfma_f32_16x16x32_bf16 v[132:135], v[176:179], v[208:211], v[132:135]
	v_mfma_f32_16x16x32_bf16 v[128:131], v[184:187], v[208:211], v[128:131]
	v_mfma_f32_16x16x32_bf16 v[116:119], v[176:179], v[216:219], v[116:119]
	v_mfma_f32_16x16x32_bf16 v[112:115], v[184:187], v[216:219], v[112:115]
	v_mfma_f32_16x16x32_bf16 v[100:103], v[176:179], v[224:227], v[100:103]
	v_mfma_f32_16x16x32_bf16 v[96:99], v[184:187], v[224:227], v[96:99]
	v_mfma_f32_16x16x32_bf16 v[84:87], v[176:179], v[240:243], v[84:87]
	v_mfma_f32_16x16x32_bf16 v[80:83], v[184:187], v[240:243], v[80:83]
	v_mfma_f32_16x16x32_bf16 v[124:127], v[188:191], v[204:207], v[124:127]
	v_mfma_f32_16x16x32_bf16 v[120:123], v[196:199], v[204:207], v[120:123]
	v_mfma_f32_16x16x32_bf16 v[108:111], v[188:191], v[212:215], v[108:111]
	v_mfma_f32_16x16x32_bf16 v[104:107], v[196:199], v[212:215], v[104:107]
	v_mfma_f32_16x16x32_bf16 v[92:95], v[188:191], v[220:223], v[92:95]
	v_mfma_f32_16x16x32_bf16 v[88:91], v[196:199], v[220:223], v[88:91]
	v_mfma_f32_16x16x32_bf16 v[76:79], v[188:191], v[236:239], v[76:79]
	v_mfma_f32_16x16x32_bf16 v[72:75], v[196:199], v[236:239], v[72:75]
	v_mfma_f32_16x16x32_bf16 v[124:127], v[192:195], v[208:211], v[124:127]
	v_mfma_f32_16x16x32_bf16 v[120:123], v[200:203], v[208:211], v[120:123]
	v_mfma_f32_16x16x32_bf16 v[108:111], v[192:195], v[216:219], v[108:111]
	v_mfma_f32_16x16x32_bf16 v[104:107], v[200:203], v[216:219], v[104:107]
	v_mfma_f32_16x16x32_bf16 v[92:95], v[192:195], v[224:227], v[92:95]
	v_mfma_f32_16x16x32_bf16 v[88:91], v[200:203], v[224:227], v[88:91]
	v_mfma_f32_16x16x32_bf16 v[76:79], v[192:195], v[240:243], v[76:79]
	v_mfma_f32_16x16x32_bf16 v[72:75], v[200:203], v[240:243], v[72:75]
	s_barrier
	s_add_u32 s74, s28, s6
	s_addc_u32 s75, s29, s7
	s_add_u32 s76, s30, s6
	s_addc_u32 s77, s31, s7
	s_sub_u32 s76, s76, 0x100000
	s_subb_u32 s77, s77, 0
	s_add_i32 s30, s71, s40
	s_mov_b32 m0, s30
	ds_read_b128 v[152:155], v166 offset:49152
	ds_read_b128 v[168:171], v166 offset:50176
	ds_read_b128 v[204:207], v166 offset:51200
	ds_read_b128 v[208:211], v166 offset:52224
	global_load_lds_dwordx4 v138, s[74:75]
	s_add_i32 m0, s30, 0x2000
	s_add_u32 s28, s28, 0x100080
	s_addc_u32 s29, s29, 0
	s_add_i32 s30, s72, s40
	global_load_lds_dwordx4 v142, s[74:75]
	s_mov_b32 m0, s30
	ds_read_b128 v[224:227], v166 offset:56320
	global_load_lds_dwordx4 v138, s[28:29]
	s_add_i32 m0, s30, 0x2000
	ds_read_b128 v[220:223], v166 offset:55296
	global_load_lds_dwordx4 v142, s[28:29]
	s_mov_b32 m0, s49
	ds_read_b128 v[216:219], v166 offset:54272
	global_load_lds_dwordx4 v136, s[76:77]
	s_mov_b32 m0, s50
	ds_read_b128 v[212:215], v166 offset:53248
	global_load_lds_dwordx4 v140, s[76:77]
	s_waitcnt vmcnt(8) lgkmcnt(0)
	s_barrier
	v_mfma_f32_16x16x32_bf16 v[68:71], v[172:175], v[152:155], v[68:71]
	v_mfma_f32_16x16x32_bf16 v[64:67], v[180:183], v[152:155], v[64:67]
	v_mfma_f32_16x16x32_bf16 v[52:55], v[172:175], v[204:207], v[52:55]
	v_mfma_f32_16x16x32_bf16 v[48:51], v[180:183], v[204:207], v[48:51]
	v_mfma_f32_16x16x32_bf16 v[36:39], v[172:175], v[212:215], v[36:39]
	v_mfma_f32_16x16x32_bf16 v[32:35], v[180:183], v[212:215], v[32:35]
	v_mfma_f32_16x16x32_bf16 v[20:23], v[172:175], v[220:223], v[20:23]
	v_mfma_f32_16x16x32_bf16 v[16:19], v[180:183], v[220:223], v[16:19]
	v_mfma_f32_16x16x32_bf16 v[68:71], v[176:179], v[168:171], v[68:71]
	v_mfma_f32_16x16x32_bf16 v[64:67], v[184:187], v[168:171], v[64:67]
	v_mfma_f32_16x16x32_bf16 v[52:55], v[176:179], v[208:211], v[52:55]
	v_mfma_f32_16x16x32_bf16 v[48:51], v[184:187], v[208:211], v[48:51]
	v_mfma_f32_16x16x32_bf16 v[36:39], v[176:179], v[216:219], v[36:39]
	v_mfma_f32_16x16x32_bf16 v[32:35], v[184:187], v[216:219], v[32:35]
	v_mfma_f32_16x16x32_bf16 v[20:23], v[176:179], v[224:227], v[20:23]
	v_mfma_f32_16x16x32_bf16 v[16:19], v[184:187], v[224:227], v[16:19]
	v_mfma_f32_16x16x32_bf16 v[60:63], v[188:191], v[152:155], v[60:63]
	v_mfma_f32_16x16x32_bf16 v[56:59], v[196:199], v[152:155], v[56:59]
	v_mfma_f32_16x16x32_bf16 v[44:47], v[188:191], v[204:207], v[44:47]
	v_mfma_f32_16x16x32_bf16 v[40:43], v[196:199], v[204:207], v[40:43]
	v_mfma_f32_16x16x32_bf16 v[28:31], v[188:191], v[212:215], v[28:31]
	v_mfma_f32_16x16x32_bf16 v[24:27], v[196:199], v[212:215], v[24:27]
	v_mfma_f32_16x16x32_bf16 v[10:13], v[188:191], v[220:223], v[12:15]
	v_mfma_f32_16x16x32_bf16 v[6:9], v[196:199], v[220:223], v[6:9]
	v_mfma_f32_16x16x32_bf16 v[60:63], v[192:195], v[168:171], v[60:63]
	v_mfma_f32_16x16x32_bf16 v[56:59], v[200:203], v[168:171], v[56:59]
	v_mfma_f32_16x16x32_bf16 v[44:47], v[192:195], v[208:211], v[44:47]
	v_mfma_f32_16x16x32_bf16 v[40:43], v[200:203], v[208:211], v[40:43]
	v_mfma_f32_16x16x32_bf16 v[28:31], v[192:195], v[216:219], v[28:31]
	v_mfma_f32_16x16x32_bf16 v[24:27], v[200:203], v[216:219], v[24:27]
	v_mfma_f32_16x16x32_bf16 v[12:15], v[192:195], v[224:227], v[10:13]
	v_mfma_f32_16x16x32_bf16 v[8:11], v[200:203], v[224:227], v[6:9]
	s_barrier
	s_add_u32 s26, s26, 0x100
	s_addc_u32 s27, s27, 0
	s_add_u32 s69, s69, 0x100
	s_addc_u32 s70, s70, 0
	s_cmp_ge_i32 s8, s63
	s_cbranch_scc0 .Lp4_top
	s_branch .Lp4_epi

.LBB0_1033:
	s_add_i32 s8, s71, 2
	s_add_u32 s28, s26, 0xfff00080
	s_addc_u32 s29, s27, -1
	s_cmp_eq_u32 s68, s71
	s_cselect_b32 s31, s64, s29
	s_cselect_b32 s30, s65, s28
	s_cselect_b32 s29, s66, s70
	s_cselect_b32 s28, s67, s69
	s_cmpk_lt_i32 s3, 0x56
	s_cselect_b32 s71, s52, 0x2b00
	s_mov_b32 s72, 0xac00
	s_cselect_b32 s74, s72, 0x4000
	s_sub_i32 s71, s71, s33
	v_min3_i32 v5, s71, v160, 2
	v_sub_u32_e32 v160, v160, v5
	v_readfirstlane_b32 s71, v5
	s_max_i32 s72, s71, 0
	s_add_i32 s72, s33, s72
	s_add_i32 s75, s72, -1
	s_min_i32 s72, s33, s75
	s_mul_hi_i32 s73, s74, s72
	s_mul_i32 s72, s74, s72
	s_add_u32 s72, s34, s72
	s_addc_u32 s73, s35, s73
	s_mul_hi_i32 s76, s74, s75
	s_mul_i32 s74, s74, s75
	s_add_u32 s74, s34, s74
	global_load_dwordx4 v[152:155], v159, s[72:73] nt
	s_addc_u32 s75, s35, s76
	global_load_dwordx4 v[168:171], v159, s[74:75] nt
	s_add_i32 s33, s71, s33
	ds_read_b128 v[172:175], v163
	ds_read_b128 v[176:179], v163 offset:1024
	ds_read_b128 v[180:183], v163 offset:2048
	ds_read_b128 v[184:187], v163 offset:3072
	ds_read_b128 v[188:191], v163 offset:16384
	ds_read_b128 v[192:195], v163 offset:17408
	ds_read_b128 v[196:199], v163 offset:18432
	ds_read_b128 v[200:203], v163 offset:19456
	s_add_i32 m0, s43, 0xc000
	ds_read_b128 v[204:207], v166
	ds_read_b128 v[208:211], v166 offset:1024
	ds_read_b128 v[212:215], v166 offset:2048
	ds_read_b128 v[216:219], v166 offset:3072
	ds_read_b128 v[220:223], v166 offset:4096
	ds_read_b128 v[224:227], v166 offset:5120
	ds_read_b128 v[236:239], v166 offset:6144
	global_load_lds_dwordx4 v146, s[26:27]
	s_add_i32 m0, s43, 0xe000
	ds_read_b128 v[240:243], v166 offset:7168
	global_load_lds_dwordx4 v148, s[26:27]
	s_waitcnt vmcnt(10) lgkmcnt(0)
	s_barrier
	v_mfma_f32_16x16x32_bf16 v[132:135], v[172:175], v[204:207], v[132:135]
	v_mfma_f32_16x16x32_bf16 v[128:131], v[180:183], v[204:207], v[128:131]
	v_mfma_f32_16x16x32_bf16 v[116:119], v[172:175], v[212:215], v[116:119]
	v_mfma_f32_16x16x32_bf16 v[112:115], v[180:183], v[212:215], v[112:115]
	v_mfma_f32_16x16x32_bf16 v[100:103], v[172:175], v[220:223], v[100:103]
	v_mfma_f32_16x16x32_bf16 v[96:99], v[180:183], v[220:223], v[96:99]
	v_mfma_f32_16x16x32_bf16 v[84:87], v[172:175], v[236:239], v[84:87]
	v_mfma_f32_16x16x32_bf16 v[80:83], v[180:183], v[236:239], v[80:83]
	v_mfma_f32_16x16x32_bf16 v[132:135], v[176:179], v[208:211], v[132:135]
	v_mfma_f32_16x16x32_bf16 v[128:131], v[184:187], v[208:211], v[128:131]
	v_mfma_f32_16x16x32_bf16 v[116:119], v[176:179], v[216:219], v[116:119]
	v_mfma_f32_16x16x32_bf16 v[112:115], v[184:187], v[216:219], v[112:115]
	v_mfma_f32_16x16x32_bf16 v[100:103], v[176:179], v[224:227], v[100:103]
	v_mfma_f32_16x16x32_bf16 v[96:99], v[184:187], v[224:227], v[96:99]
	v_mfma_f32_16x16x32_bf16 v[84:87], v[176:179], v[240:243], v[84:87]
	v_mfma_f32_16x16x32_bf16 v[80:83], v[184:187], v[240:243], v[80:83]
	v_mfma_f32_16x16x32_bf16 v[124:127], v[188:191], v[204:207], v[124:127]
	v_mfma_f32_16x16x32_bf16 v[120:123], v[196:199], v[204:207], v[120:123]
	v_mfma_f32_16x16x32_bf16 v[108:111], v[188:191], v[212:215], v[108:111]
	v_mfma_f32_16x16x32_bf16 v[104:107], v[196:199], v[212:215], v[104:107]
	v_mfma_f32_16x16x32_bf16 v[92:95], v[188:191], v[220:223], v[92:95]
	v_mfma_f32_16x16x32_bf16 v[88:91], v[196:199], v[220:223], v[88:91]
	v_mfma_f32_16x16x32_bf16 v[76:79], v[188:191], v[236:239], v[76:79]
	v_mfma_f32_16x16x32_bf16 v[72:75], v[196:199], v[236:239], v[72:75]
	v_mfma_f32_16x16x32_bf16 v[124:127], v[192:195], v[208:211], v[124:127]
	v_mfma_f32_16x16x32_bf16 v[120:123], v[200:203], v[208:211], v[120:123]
	v_mfma_f32_16x16x32_bf16 v[108:111], v[192:195], v[216:219], v[108:111]
	v_mfma_f32_16x16x32_bf16 v[104:107], v[200:203], v[216:219], v[104:107]
	v_mfma_f32_16x16x32_bf16 v[92:95], v[192:195], v[224:227], v[92:95]
	v_mfma_f32_16x16x32_bf16 v[88:91], v[200:203], v[224:227], v[88:91]
	v_mfma_f32_16x16x32_bf16 v[76:79], v[192:195], v[240:243], v[76:79]
	v_mfma_f32_16x16x32_bf16 v[72:75], v[200:203], v[240:243], v[72:75]
	s_barrier
	s_add_i32 s71, s53, s40
	s_mov_b32 m0, s71
	ds_read_b128 v[204:207], v166 offset:16384
	ds_read_b128 v[208:211], v166 offset:17408
	ds_read_b128 v[212:215], v166 offset:18432
	ds_read_b128 v[216:219], v166 offset:19456
	global_load_lds_dwordx4 v138, s[28:29]
	s_add_i32 m0, s71, 0x2000
	s_add_u32 s72, s28, 0x100000
	s_addc_u32 s73, s29, 0
	s_add_i32 s71, s54, s40
	global_load_lds_dwordx4 v142, s[28:29]
	s_mov_b32 m0, s71
	ds_read_b128 v[240:243], v166 offset:23552
	global_load_lds_dwordx4 v138, s[72:73]
	s_add_i32 m0, s71, 0x2000
	ds_read_b128 v[236:239], v166 offset:22528
	global_load_lds_dwordx4 v142, s[72:73]
	s_mov_b32 m0, s43
	ds_read_b128 v[224:227], v166 offset:21504
	global_load_lds_dwordx4 v136, s[30:31]
	s_mov_b32 m0, s44
	ds_read_b128 v[220:223], v166 offset:20480
	global_load_lds_dwordx4 v140, s[30:31]
	s_waitcnt vmcnt(10) lgkmcnt(0)
	s_barrier
	v_mfma_f32_16x16x32_bf16 v[68:71], v[172:175], v[204:207], v[68:71]
	v_mfma_f32_16x16x32_bf16 v[64:67], v[180:183], v[204:207], v[64:67]
	v_mfma_f32_16x16x32_bf16 v[52:55], v[172:175], v[212:215], v[52:55]
	v_mfma_f32_16x16x32_bf16 v[48:51], v[180:183], v[212:215], v[48:51]
	v_mfma_f32_16x16x32_bf16 v[36:39], v[172:175], v[220:223], v[36:39]
	v_mfma_f32_16x16x32_bf16 v[32:35], v[180:183], v[220:223], v[32:35]
	v_mfma_f32_16x16x32_bf16 v[20:23], v[172:175], v[236:239], v[20:23]
	v_mfma_f32_16x16x32_bf16 v[16:19], v[180:183], v[236:239], v[16:19]
	v_mfma_f32_16x16x32_bf16 v[68:71], v[176:179], v[208:211], v[68:71]
	v_mfma_f32_16x16x32_bf16 v[64:67], v[184:187], v[208:211], v[64:67]
	v_mfma_f32_16x16x32_bf16 v[52:55], v[176:179], v[216:219], v[52:55]
	v_mfma_f32_16x16x32_bf16 v[48:51], v[184:187], v[216:219], v[48:51]
	v_mfma_f32_16x16x32_bf16 v[36:39], v[176:179], v[224:227], v[36:39]
	v_mfma_f32_16x16x32_bf16 v[32:35], v[184:187], v[224:227], v[32:35]
	v_mfma_f32_16x16x32_bf16 v[20:23], v[176:179], v[240:243], v[20:23]
	v_mfma_f32_16x16x32_bf16 v[16:19], v[184:187], v[240:243], v[16:19]
	v_mfma_f32_16x16x32_bf16 v[60:63], v[188:191], v[204:207], v[60:63]
	v_mfma_f32_16x16x32_bf16 v[56:59], v[196:199], v[204:207], v[56:59]
	v_mfma_f32_16x16x32_bf16 v[44:47], v[188:191], v[212:215], v[44:47]
	v_mfma_f32_16x16x32_bf16 v[40:43], v[196:199], v[212:215], v[40:43]
	v_mfma_f32_16x16x32_bf16 v[28:31], v[188:191], v[220:223], v[28:31]
	v_mfma_f32_16x16x32_bf16 v[24:27], v[196:199], v[220:223], v[24:27]
	v_mfma_f32_16x16x32_bf16 v[12:15], v[188:191], v[236:239], v[12:15]
	v_mfma_f32_16x16x32_bf16 v[6:9], v[196:199], v[236:239], v[8:11]
	v_mfma_f32_16x16x32_bf16 v[60:63], v[192:195], v[208:211], v[60:63]
	v_mfma_f32_16x16x32_bf16 v[56:59], v[200:203], v[208:211], v[56:59]
	v_mfma_f32_16x16x32_bf16 v[44:47], v[192:195], v[216:219], v[44:47]
	v_mfma_f32_16x16x32_bf16 v[40:43], v[200:203], v[216:219], v[40:43]
	v_mfma_f32_16x16x32_bf16 v[28:31], v[192:195], v[224:227], v[28:31]
	v_mfma_f32_16x16x32_bf16 v[24:27], v[200:203], v[224:227], v[24:27]
	v_mfma_f32_16x16x32_bf16 v[12:15], v[192:195], v[240:243], v[12:15]
	v_mfma_f32_16x16x32_bf16 v[6:9], v[200:203], v[240:243], v[6:9]
	s_barrier
	s_add_i32 s71, 0, 0x18000
	s_add_i32 s72, 0, 0x1c000
	ds_read_b128 v[172:175], v163 offset:32768
	ds_read_b128 v[176:179], v163 offset:33792
	ds_read_b128 v[180:183], v163 offset:34816
	ds_read_b128 v[184:187], v163 offset:35840
	ds_read_b128 v[188:191], v163 offset:49152
	ds_read_b128 v[192:195], v163 offset:50176
	ds_read_b128 v[196:199], v163 offset:51200
	ds_read_b128 v[200:203], v163 offset:52224
	s_add_u32 s30, s30, 0x100000
	s_addc_u32 s31, s31, 0
	s_mov_b32 m0, s45
	ds_read_b128 v[204:207], v166 offset:32768
	ds_read_b128 v[208:211], v166 offset:33792
	ds_read_b128 v[212:215], v166 offset:34816
	ds_read_b128 v[216:219], v166 offset:35840
	ds_read_b128 v[220:223], v166 offset:36864
	ds_read_b128 v[224:227], v166 offset:37888
	ds_read_b128 v[236:239], v166 offset:38912
	global_load_lds_dwordx4 v136, s[30:31]
	s_mov_b32 m0, s46
	ds_read_b128 v[240:243], v166 offset:39936
	global_load_lds_dwordx4 v140, s[30:31]
	s_waitcnt vmcnt(8) lgkmcnt(0)
	s_barrier
	v_mfma_f32_16x16x32_bf16 v[132:135], v[172:175], v[204:207], v[132:135]
	v_mfma_f32_16x16x32_bf16 v[128:131], v[180:183], v[204:207], v[128:131]
	v_mfma_f32_16x16x32_bf16 v[116:119], v[172:175], v[212:215], v[116:119]
	v_mfma_f32_16x16x32_bf16 v[112:115], v[180:183], v[212:215], v[112:115]
	v_mfma_f32_16x16x32_bf16 v[100:103], v[172:175], v[220:223], v[100:103]
	v_max3_f32 v0, v0, |v152|, |v168|
	v_mfma_f32_16x16x32_bf16 v[96:99], v[180:183], v[220:223], v[96:99]
	v_max3_f32 v1, v1, |v153|, |v169|
	v_mfma_f32_16x16x32_bf16 v[84:87], v[172:175], v[236:239], v[84:87]
	v_max3_f32 v2, v2, |v154|, |v170|
	v_mfma_f32_16x16x32_bf16 v[80:83], v[180:183], v[236:239], v[80:83]
	v_max3_f32 v3, v3, |v155|, |v171|
	v_mfma_f32_16x16x32_bf16 v[132:135], v[176:179], v[208:211], v[132:135]
	v_mfma_f32_16x16x32_bf16 v[128:131], v[184:187], v[208:211], v[128:131]
	v_mfma_f32_16x16x32_bf16 v[116:119], v[176:179], v[216:219], v[116:119]
	v_mfma_f32_16x16x32_bf16 v[112:115], v[184:187], v[216:219], v[112:115]
	v_mfma_f32_16x16x32_bf16 v[100:103], v[176:179], v[224:227], v[100:103]
	v_mfma_f32_16x16x32_bf16 v[96:99], v[184:187], v[224:227], v[96:99]
	v_mfma_f32_16x16x32_bf16 v[84:87], v[176:179], v[240:243], v[84:87]
	v_mfma_f32_16x16x32_bf16 v[80:83], v[184:187], v[240:243], v[80:83]
	v_mfma_f32_16x16x32_bf16 v[124:127], v[188:191], v[204:207], v[124:127]
	v_mfma_f32_16x16x32_bf16 v[120:123], v[196:199], v[204:207], v[120:123]
	v_mfma_f32_16x16x32_bf16 v[108:111], v[188:191], v[212:215], v[108:111]
	v_mfma_f32_16x16x32_bf16 v[104:107], v[196:199], v[212:215], v[104:107]
	v_mfma_f32_16x16x32_bf16 v[92:95], v[188:191], v[220:223], v[92:95]
	v_mfma_f32_16x16x32_bf16 v[88:91], v[196:199], v[220:223], v[88:91]
	v_mfma_f32_16x16x32_bf16 v[76:79], v[188:191], v[236:239], v[76:79]
	v_mfma_f32_16x16x32_bf16 v[72:75], v[196:199], v[236:239], v[72:75]
	v_mfma_f32_16x16x32_bf16 v[124:127], v[192:195], v[208:211], v[124:127]
	v_mfma_f32_16x16x32_bf16 v[120:123], v[200:203], v[208:211], v[120:123]
	v_mfma_f32_16x16x32_bf16 v[108:111], v[192:195], v[216:219], v[108:111]
	v_mfma_f32_16x16x32_bf16 v[104:107], v[200:203], v[216:219], v[104:107]
	v_mfma_f32_16x16x32_bf16 v[92:95], v[192:195], v[224:227], v[92:95]
	v_mfma_f32_16x16x32_bf16 v[88:91], v[200:203], v[224:227], v[88:91]
	v_mfma_f32_16x16x32_bf16 v[76:79], v[192:195], v[240:243], v[76:79]
	v_mfma_f32_16x16x32_bf16 v[72:75], v[200:203], v[240:243], v[72:75]
	s_barrier
	s_add_u32 s74, s28, s6
	s_addc_u32 s75, s29, s7
	s_add_u32 s76, s30, s6
	s_addc_u32 s77, s31, s7
	s_sub_u32 s76, s76, 0x100000
	s_subb_u32 s77, s77, 0
	s_add_i32 s30, s71, s40
	s_mov_b32 m0, s30
	ds_read_b128 v[152:155], v166 offset:49152
	ds_read_b128 v[168:171], v166 offset:50176
	ds_read_b128 v[204:207], v166 offset:51200
	ds_read_b128 v[208:211], v166 offset:52224
	global_load_lds_dwordx4 v138, s[74:75]
	s_add_i32 m0, s30, 0x2000
	s_add_u32 s28, s28, 0x100080
	s_addc_u32 s29, s29, 0
	s_add_i32 s30, s72, s40
	global_load_lds_dwordx4 v142, s[74:75]
	s_mov_b32 m0, s30
	ds_read_b128 v[224:227], v166 offset:56320
	global_load_lds_dwordx4 v138, s[28:29]
	s_add_i32 m0, s30, 0x2000
	ds_read_b128 v[220:223], v166 offset:55296
	global_load_lds_dwordx4 v142, s[28:29]
	s_mov_b32 m0, s49
	ds_read_b128 v[216:219], v166 offset:54272
	global_load_lds_dwordx4 v136, s[76:77]
	s_mov_b32 m0, s50
	ds_read_b128 v[212:215], v166 offset:53248
	global_load_lds_dwordx4 v140, s[76:77]
	s_waitcnt vmcnt(8) lgkmcnt(0)
	s_barrier
	v_mfma_f32_16x16x32_bf16 v[68:71], v[172:175], v[152:155], v[68:71]
	v_mfma_f32_16x16x32_bf16 v[64:67], v[180:183], v[152:155], v[64:67]
	v_mfma_f32_16x16x32_bf16 v[52:55], v[172:175], v[204:207], v[52:55]
	v_mfma_f32_16x16x32_bf16 v[48:51], v[180:183], v[204:207], v[48:51]
	v_mfma_f32_16x16x32_bf16 v[36:39], v[172:175], v[212:215], v[36:39]
	v_mfma_f32_16x16x32_bf16 v[32:35], v[180:183], v[212:215], v[32:35]
	v_mfma_f32_16x16x32_bf16 v[20:23], v[172:175], v[220:223], v[20:23]
	v_mfma_f32_16x16x32_bf16 v[16:19], v[180:183], v[220:223], v[16:19]
	v_mfma_f32_16x16x32_bf16 v[68:71], v[176:179], v[168:171], v[68:71]
	v_mfma_f32_16x16x32_bf16 v[64:67], v[184:187], v[168:171], v[64:67]
	v_mfma_f32_16x16x32_bf16 v[52:55], v[176:179], v[208:211], v[52:55]
	v_mfma_f32_16x16x32_bf16 v[48:51], v[184:187], v[208:211], v[48:51]
	v_mfma_f32_16x16x32_bf16 v[36:39], v[176:179], v[216:219], v[36:39]
	v_mfma_f32_16x16x32_bf16 v[32:35], v[184:187], v[216:219], v[32:35]
	v_mfma_f32_16x16x32_bf16 v[20:23], v[176:179], v[224:227], v[20:23]
	v_mfma_f32_16x16x32_bf16 v[16:19], v[184:187], v[224:227], v[16:19]
	v_mfma_f32_16x16x32_bf16 v[60:63], v[188:191], v[152:155], v[60:63]
	v_mfma_f32_16x16x32_bf16 v[56:59], v[196:199], v[152:155], v[56:59]
	v_mfma_f32_16x16x32_bf16 v[44:47], v[188:191], v[204:207], v[44:47]
	v_mfma_f32_16x16x32_bf16 v[40:43], v[196:199], v[204:207], v[40:43]
	v_mfma_f32_16x16x32_bf16 v[28:31], v[188:191], v[212:215], v[28:31]
	v_mfma_f32_16x16x32_bf16 v[24:27], v[196:199], v[212:215], v[24:27]
	v_mfma_f32_16x16x32_bf16 v[10:13], v[188:191], v[220:223], v[12:15]
	v_mfma_f32_16x16x32_bf16 v[6:9], v[196:199], v[220:223], v[6:9]
	v_mfma_f32_16x16x32_bf16 v[60:63], v[192:195], v[168:171], v[60:63]
	v_mfma_f32_16x16x32_bf16 v[56:59], v[200:203], v[168:171], v[56:59]
	v_mfma_f32_16x16x32_bf16 v[44:47], v[192:195], v[208:211], v[44:47]
	v_mfma_f32_16x16x32_bf16 v[40:43], v[200:203], v[208:211], v[40:43]
	v_mfma_f32_16x16x32_bf16 v[28:31], v[192:195], v[216:219], v[28:31]
	v_mfma_f32_16x16x32_bf16 v[24:27], v[200:203], v[216:219], v[24:27]
	v_mfma_f32_16x16x32_bf16 v[12:15], v[192:195], v[224:227], v[10:13]
	v_mfma_f32_16x16x32_bf16 v[8:11], v[200:203], v[224:227], v[6:9]
	s_barrier
	s_add_u32 s26, s26, 0x100
	s_addc_u32 s27, s27, 0
	s_add_u32 s69, s69, 0x100
	s_addc_u32 s70, s70, 0
	s_cmp_ge_i32 s8, s63
	s_cbranch_scc0 .LBB0_1018

.LBB0_1238:
	s_add_i32 s74, s38, 2
	s_add_u32 s39, s36, 0xfff80080
	s_addc_u32 s40, s37, -1
	s_cmp_eq_u32 s71, s38
	s_cselect_b32 s41, s67, s40
	s_cselect_b32 s40, s68, s39
	ds_read_b128 v[140:143], v177
	ds_read_b128 v[144:147], v177 offset:1024
	ds_read_b128 v[148:151], v177 offset:2048
	ds_read_b128 v[152:155], v177 offset:3072
	ds_read_b128 v[156:159], v177 offset:16384
	ds_read_b128 v[160:163], v177 offset:17408
	ds_read_b128 v[164:167], v177 offset:18432
	ds_read_b128 v[168:171], v177 offset:19456
	s_cselect_b32 s38, s70, s72
	s_cselect_b32 s39, s69, s73
	s_add_i32 m0, s45, 0xc000
	ds_read_b128 v[180:183], v178
	ds_read_b128 v[184:187], v178 offset:1024
	ds_read_b128 v[188:191], v178 offset:2048
	ds_read_b128 v[192:195], v178 offset:3072
	ds_read_b128 v[196:199], v178 offset:4096
	ds_read_b128 v[200:203], v178 offset:5120
	ds_read_b128 v[204:207], v178 offset:6144
	global_load_lds_dwordx4 v136, s[36:37]
	s_add_i32 m0, s45, 0xe000
	ds_read_b128 v[208:211], v178 offset:7168
	global_load_lds_dwordx4 v138, s[36:37]
	s_waitcnt vmcnt(8) lgkmcnt(0)
	s_barrier
	v_mfma_i32_16x16x64_i8 v[124:127], v[140:143], v[180:183], v[124:127]
	v_mfma_i32_16x16x64_i8 v[120:123], v[148:151], v[180:183], v[120:123]
	v_mfma_i32_16x16x64_i8 v[116:119], v[140:143], v[188:191], v[116:119]
	v_mfma_i32_16x16x64_i8 v[112:115], v[148:151], v[188:191], v[112:115]
	v_mfma_i32_16x16x64_i8 v[104:107], v[140:143], v[196:199], v[104:107]
	v_mfma_i32_16x16x64_i8 v[96:99], v[148:151], v[196:199], v[96:99]
	v_mfma_i32_16x16x64_i8 v[88:91], v[140:143], v[204:207], v[88:91]
	v_mfma_i32_16x16x64_i8 v[80:83], v[148:151], v[204:207], v[80:83]
	v_mfma_i32_16x16x64_i8 v[124:127], v[144:147], v[184:187], v[124:127]
	v_mfma_i32_16x16x64_i8 v[120:123], v[152:155], v[184:187], v[120:123]
	v_mfma_i32_16x16x64_i8 v[116:119], v[144:147], v[192:195], v[116:119]
	v_mfma_i32_16x16x64_i8 v[112:115], v[152:155], v[192:195], v[112:115]
	v_mfma_i32_16x16x64_i8 v[104:107], v[144:147], v[200:203], v[104:107]
	v_mfma_i32_16x16x64_i8 v[96:99], v[152:155], v[200:203], v[96:99]
	v_mfma_i32_16x16x64_i8 v[88:91], v[144:147], v[208:211], v[88:91]
	v_mfma_i32_16x16x64_i8 v[80:83], v[152:155], v[208:211], v[80:83]
	v_mfma_i32_16x16x64_i8 v[108:111], v[156:159], v[180:183], v[108:111]
	v_mfma_i32_16x16x64_i8 v[100:103], v[164:167], v[180:183], v[100:103]
	v_mfma_i32_16x16x64_i8 v[92:95], v[156:159], v[188:191], v[92:95]
	v_mfma_i32_16x16x64_i8 v[84:87], v[164:167], v[188:191], v[84:87]
	v_mfma_i32_16x16x64_i8 v[76:79], v[156:159], v[196:199], v[76:79]
	v_mfma_i32_16x16x64_i8 v[72:75], v[164:167], v[196:199], v[72:75]
	v_mfma_i32_16x16x64_i8 v[68:71], v[156:159], v[204:207], v[68:71]
	v_mfma_i32_16x16x64_i8 v[64:67], v[164:167], v[204:207], v[64:67]
	v_mfma_i32_16x16x64_i8 v[108:111], v[160:163], v[184:187], v[108:111]
	v_mfma_i32_16x16x64_i8 v[100:103], v[168:171], v[184:187], v[100:103]
	v_mfma_i32_16x16x64_i8 v[92:95], v[160:163], v[192:195], v[92:95]
	v_mfma_i32_16x16x64_i8 v[84:87], v[168:171], v[192:195], v[84:87]
	v_mfma_i32_16x16x64_i8 v[76:79], v[160:163], v[200:203], v[76:79]
	v_mfma_i32_16x16x64_i8 v[72:75], v[168:171], v[200:203], v[72:75]
	v_mfma_i32_16x16x64_i8 v[68:71], v[160:163], v[208:211], v[68:71]
	v_mfma_i32_16x16x64_i8 v[64:67], v[168:171], v[208:211], v[64:67]
	s_barrier
	s_add_i32 s75, s55, s42
	s_mov_b32 m0, s75
	ds_read_b128 v[180:183], v178 offset:16384
	ds_read_b128 v[184:187], v178 offset:17408
	ds_read_b128 v[188:191], v178 offset:18432
	ds_read_b128 v[192:195], v178 offset:19456
	global_load_lds_dwordx4 v130, s[38:39]
	s_add_i32 m0, s75, 0x2000
	s_add_u32 s76, s38, 0x80000
	s_addc_u32 s77, s39, 0
	s_add_i32 s75, s60, s42
	global_load_lds_dwordx4 v134, s[38:39]
	s_mov_b32 m0, s75
	ds_read_b128 v[208:211], v178 offset:23552
	global_load_lds_dwordx4 v130, s[76:77]
	s_add_i32 m0, s75, 0x2000
	ds_read_b128 v[204:207], v178 offset:22528
	global_load_lds_dwordx4 v134, s[76:77]
	s_mov_b32 m0, s45
	ds_read_b128 v[200:203], v178 offset:21504
	global_load_lds_dwordx4 v128, s[40:41]
	s_mov_b32 m0, s46
	ds_read_b128 v[196:199], v178 offset:20480
	global_load_lds_dwordx4 v132, s[40:41]
	s_waitcnt vmcnt(8) lgkmcnt(0)
	s_barrier
	v_mfma_i32_16x16x64_i8 v[60:63], v[140:143], v[180:183], v[60:63]
	v_mfma_i32_16x16x64_i8 v[56:59], v[148:151], v[180:183], v[56:59]
	v_mfma_i32_16x16x64_i8 v[52:55], v[140:143], v[188:191], v[52:55]
	v_mfma_i32_16x16x64_i8 v[48:51], v[148:151], v[188:191], v[48:51]
	v_mfma_i32_16x16x64_i8 v[40:43], v[140:143], v[196:199], v[40:43]
	v_mfma_i32_16x16x64_i8 v[32:35], v[148:151], v[196:199], v[32:35]
	v_mfma_i32_16x16x64_i8 v[24:27], v[140:143], v[204:207], v[24:27]
	v_mfma_i32_16x16x64_i8 v[16:19], v[148:151], v[204:207], v[16:19]
	v_mfma_i32_16x16x64_i8 v[60:63], v[144:147], v[184:187], v[60:63]
	v_mfma_i32_16x16x64_i8 v[56:59], v[152:155], v[184:187], v[56:59]
	v_mfma_i32_16x16x64_i8 v[52:55], v[144:147], v[192:195], v[52:55]
	v_mfma_i32_16x16x64_i8 v[48:51], v[152:155], v[192:195], v[48:51]
	v_mfma_i32_16x16x64_i8 v[40:43], v[144:147], v[200:203], v[40:43]
	v_mfma_i32_16x16x64_i8 v[32:35], v[152:155], v[200:203], v[32:35]
	v_mfma_i32_16x16x64_i8 v[24:27], v[144:147], v[208:211], v[24:27]
	v_mfma_i32_16x16x64_i8 v[16:19], v[152:155], v[208:211], v[16:19]
	v_mfma_i32_16x16x64_i8 v[44:47], v[156:159], v[180:183], v[44:47]
	v_mfma_i32_16x16x64_i8 v[36:39], v[164:167], v[180:183], v[36:39]
	v_mfma_i32_16x16x64_i8 v[28:31], v[156:159], v[188:191], v[28:31]
	v_mfma_i32_16x16x64_i8 v[20:23], v[164:167], v[188:191], v[20:23]
	v_mfma_i32_16x16x64_i8 v[12:15], v[156:159], v[196:199], v[12:15]
	v_mfma_i32_16x16x64_i8 v[8:11], v[164:167], v[196:199], v[8:11]
	v_mfma_i32_16x16x64_i8 v[4:7], v[156:159], v[204:207], v[4:7]
	v_mfma_i32_16x16x64_i8 v[0:3], v[164:167], v[204:207], v[0:3]
	v_mfma_i32_16x16x64_i8 v[44:47], v[160:163], v[184:187], v[44:47]
	v_mfma_i32_16x16x64_i8 v[36:39], v[168:171], v[184:187], v[36:39]
	v_mfma_i32_16x16x64_i8 v[28:31], v[160:163], v[192:195], v[28:31]
	v_mfma_i32_16x16x64_i8 v[20:23], v[168:171], v[192:195], v[20:23]
	v_mfma_i32_16x16x64_i8 v[12:15], v[160:163], v[200:203], v[12:15]
	v_mfma_i32_16x16x64_i8 v[8:11], v[168:171], v[200:203], v[8:11]
	v_mfma_i32_16x16x64_i8 v[4:7], v[160:163], v[208:211], v[4:7]
	v_mfma_i32_16x16x64_i8 v[0:3], v[168:171], v[208:211], v[0:3]
	s_barrier
	s_add_i32 s75, 0, 0x18000
	s_add_i32 s76, 0, 0x1c000
	ds_read_b128 v[140:143], v177 offset:32768
	ds_read_b128 v[144:147], v177 offset:33792
	ds_read_b128 v[148:151], v177 offset:34816
	ds_read_b128 v[152:155], v177 offset:35840
	ds_read_b128 v[156:159], v177 offset:49152
	ds_read_b128 v[160:163], v177 offset:50176
	ds_read_b128 v[164:167], v177 offset:51200
	ds_read_b128 v[168:171], v177 offset:52224
	s_add_u32 s40, s40, 0x80000
	s_addc_u32 s41, s41, 0
	s_mov_b32 m0, s47
	ds_read_b128 v[180:183], v178 offset:32768
	ds_read_b128 v[184:187], v178 offset:33792
	ds_read_b128 v[188:191], v178 offset:34816
	ds_read_b128 v[192:195], v178 offset:35840
	ds_read_b128 v[196:199], v178 offset:36864
	ds_read_b128 v[200:203], v178 offset:37888
	ds_read_b128 v[204:207], v178 offset:38912
	global_load_lds_dwordx4 v128, s[40:41]
	s_mov_b32 m0, s48
	ds_read_b128 v[208:211], v178 offset:39936
	global_load_lds_dwordx4 v132, s[40:41]
	s_waitcnt vmcnt(8) lgkmcnt(0)
	s_barrier
	v_mfma_i32_16x16x64_i8 v[124:127], v[140:143], v[180:183], v[124:127]
	v_mfma_i32_16x16x64_i8 v[120:123], v[148:151], v[180:183], v[120:123]
	v_mfma_i32_16x16x64_i8 v[116:119], v[140:143], v[188:191], v[116:119]
	v_mfma_i32_16x16x64_i8 v[112:115], v[148:151], v[188:191], v[112:115]
	v_mfma_i32_16x16x64_i8 v[104:107], v[140:143], v[196:199], v[104:107]
	v_mfma_i32_16x16x64_i8 v[96:99], v[148:151], v[196:199], v[96:99]
	v_mfma_i32_16x16x64_i8 v[88:91], v[140:143], v[204:207], v[88:91]
	v_mfma_i32_16x16x64_i8 v[80:83], v[148:151], v[204:207], v[80:83]
	v_mfma_i32_16x16x64_i8 v[124:127], v[144:147], v[184:187], v[124:127]
	v_mfma_i32_16x16x64_i8 v[120:123], v[152:155], v[184:187], v[120:123]
	v_mfma_i32_16x16x64_i8 v[116:119], v[144:147], v[192:195], v[116:119]
	v_mfma_i32_16x16x64_i8 v[112:115], v[152:155], v[192:195], v[112:115]
	v_mfma_i32_16x16x64_i8 v[104:107], v[144:147], v[200:203], v[104:107]
	v_mfma_i32_16x16x64_i8 v[96:99], v[152:155], v[200:203], v[96:99]
	v_mfma_i32_16x16x64_i8 v[88:91], v[144:147], v[208:211], v[88:91]
	v_mfma_i32_16x16x64_i8 v[80:83], v[152:155], v[208:211], v[80:83]
	v_mfma_i32_16x16x64_i8 v[108:111], v[156:159], v[180:183], v[108:111]
	v_mfma_i32_16x16x64_i8 v[100:103], v[164:167], v[180:183], v[100:103]
	v_mfma_i32_16x16x64_i8 v[92:95], v[156:159], v[188:191], v[92:95]
	v_mfma_i32_16x16x64_i8 v[84:87], v[164:167], v[188:191], v[84:87]
	v_mfma_i32_16x16x64_i8 v[76:79], v[156:159], v[196:199], v[76:79]
	v_mfma_i32_16x16x64_i8 v[72:75], v[164:167], v[196:199], v[72:75]
	v_mfma_i32_16x16x64_i8 v[68:71], v[156:159], v[204:207], v[68:71]
	v_mfma_i32_16x16x64_i8 v[64:67], v[164:167], v[204:207], v[64:67]
	v_mfma_i32_16x16x64_i8 v[108:111], v[160:163], v[184:187], v[108:111]
	v_mfma_i32_16x16x64_i8 v[100:103], v[168:171], v[184:187], v[100:103]
	v_mfma_i32_16x16x64_i8 v[92:95], v[160:163], v[192:195], v[92:95]
	v_mfma_i32_16x16x64_i8 v[84:87], v[168:171], v[192:195], v[84:87]
	v_mfma_i32_16x16x64_i8 v[76:79], v[160:163], v[200:203], v[76:79]
	v_mfma_i32_16x16x64_i8 v[72:75], v[168:171], v[200:203], v[72:75]
	v_mfma_i32_16x16x64_i8 v[68:71], v[160:163], v[208:211], v[68:71]
	v_mfma_i32_16x16x64_i8 v[64:67], v[168:171], v[208:211], v[64:67]
	s_barrier
	s_add_u32 s98, s38, s20
	s_addc_u32 s99, s39, s21
	s_add_u32 s100, s40, s20
	s_addc_u32 s101, s41, s21
	s_sub_u32 s100, s100, 0x80000
	s_subb_u32 s101, s101, 0
	s_add_i32 s40, s75, s42
	s_mov_b32 m0, s40
	ds_read_b128 v[180:183], v178 offset:49152
	ds_read_b128 v[184:187], v178 offset:50176
	ds_read_b128 v[188:191], v178 offset:51200
	ds_read_b128 v[192:195], v178 offset:52224
	global_load_lds_dwordx4 v130, s[98:99]
	s_add_i32 m0, s40, 0x2000
	s_add_u32 s38, s38, 0x80080
	s_addc_u32 s39, s39, 0
	s_add_i32 s40, s76, s42
	global_load_lds_dwordx4 v134, s[98:99]
	s_mov_b32 m0, s40
	ds_read_b128 v[208:211], v178 offset:56320
	global_load_lds_dwordx4 v130, s[38:39]
	s_add_i32 m0, s40, 0x2000
	ds_read_b128 v[204:207], v178 offset:55296
	global_load_lds_dwordx4 v134, s[38:39]
	s_mov_b32 m0, s51
	ds_read_b128 v[200:203], v178 offset:54272
	global_load_lds_dwordx4 v128, s[100:101]
	s_mov_b32 m0, s52
	ds_read_b128 v[196:199], v178 offset:53248
	global_load_lds_dwordx4 v132, s[100:101]
	s_waitcnt vmcnt(8) lgkmcnt(0)
	s_barrier
	v_mfma_i32_16x16x64_i8 v[60:63], v[140:143], v[180:183], v[60:63]
	v_mfma_i32_16x16x64_i8 v[56:59], v[148:151], v[180:183], v[56:59]
	v_mfma_i32_16x16x64_i8 v[52:55], v[140:143], v[188:191], v[52:55]
	v_mfma_i32_16x16x64_i8 v[48:51], v[148:151], v[188:191], v[48:51]
	v_mfma_i32_16x16x64_i8 v[40:43], v[140:143], v[196:199], v[40:43]
	v_mfma_i32_16x16x64_i8 v[32:35], v[148:151], v[196:199], v[32:35]
	v_mfma_i32_16x16x64_i8 v[24:27], v[140:143], v[204:207], v[24:27]
	v_mfma_i32_16x16x64_i8 v[16:19], v[148:151], v[204:207], v[16:19]
	v_mfma_i32_16x16x64_i8 v[60:63], v[144:147], v[184:187], v[60:63]
	v_mfma_i32_16x16x64_i8 v[56:59], v[152:155], v[184:187], v[56:59]
	v_mfma_i32_16x16x64_i8 v[52:55], v[144:147], v[192:195], v[52:55]
	v_mfma_i32_16x16x64_i8 v[48:51], v[152:155], v[192:195], v[48:51]
	v_mfma_i32_16x16x64_i8 v[40:43], v[144:147], v[200:203], v[40:43]
	v_mfma_i32_16x16x64_i8 v[32:35], v[152:155], v[200:203], v[32:35]
	v_mfma_i32_16x16x64_i8 v[24:27], v[144:147], v[208:211], v[24:27]
	v_mfma_i32_16x16x64_i8 v[16:19], v[152:155], v[208:211], v[16:19]
	v_mfma_i32_16x16x64_i8 v[44:47], v[156:159], v[180:183], v[44:47]
	v_mfma_i32_16x16x64_i8 v[36:39], v[164:167], v[180:183], v[36:39]
	v_mfma_i32_16x16x64_i8 v[28:31], v[156:159], v[188:191], v[28:31]
	v_mfma_i32_16x16x64_i8 v[20:23], v[164:167], v[188:191], v[20:23]
	v_mfma_i32_16x16x64_i8 v[12:15], v[156:159], v[196:199], v[12:15]
	v_mfma_i32_16x16x64_i8 v[8:11], v[164:167], v[196:199], v[8:11]
	v_mfma_i32_16x16x64_i8 v[4:7], v[156:159], v[204:207], v[4:7]
	v_mfma_i32_16x16x64_i8 v[0:3], v[164:167], v[204:207], v[0:3]
	v_mfma_i32_16x16x64_i8 v[44:47], v[160:163], v[184:187], v[44:47]
	v_mfma_i32_16x16x64_i8 v[36:39], v[168:171], v[184:187], v[36:39]
	v_mfma_i32_16x16x64_i8 v[28:31], v[160:163], v[192:195], v[28:31]
	v_mfma_i32_16x16x64_i8 v[20:23], v[168:171], v[192:195], v[20:23]
	v_mfma_i32_16x16x64_i8 v[12:15], v[160:163], v[200:203], v[12:15]
	v_mfma_i32_16x16x64_i8 v[8:11], v[168:171], v[200:203], v[8:11]
	v_mfma_i32_16x16x64_i8 v[4:7], v[160:163], v[208:211], v[4:7]
	v_mfma_i32_16x16x64_i8 v[0:3], v[168:171], v[208:211], v[0:3]
	s_barrier
	s_add_u32 s36, s36, 0x100
	s_addc_u32 s37, s37, 0
	s_add_u32 s72, s72, 0x100
	s_addc_u32 s73, s73, 0
	s_cmp_ge_i32 s74, s8
	s_mov_b32 s38, s74
	s_cbranch_scc0 .LBB0_1238

.Lq_body_L:
	s_add_i32 s74, s38, 2
	s_add_u32 s39, s36, 0xfff80080
	s_addc_u32 s40, s37, -1
	s_cmp_eq_u32 s71, s38
	s_cselect_b32 s41, s67, s40
	s_cselect_b32 s40, s68, s39
	ds_read_b128 v[140:143], v177
	ds_read_b128 v[144:147], v177 offset:1024
	ds_read_b128 v[148:151], v177 offset:2048
	ds_read_b128 v[152:155], v177 offset:3072
	ds_read_b128 v[156:159], v177 offset:16384
	ds_read_b128 v[160:163], v177 offset:17408
	ds_read_b128 v[164:167], v177 offset:18432
	ds_read_b128 v[168:171], v177 offset:19456
	s_cselect_b32 s38, s70, s72
	s_cselect_b32 s39, s69, s73
	s_add_i32 m0, s45, 0xc000
	ds_read_b128 v[180:183], v178
	ds_read_b128 v[184:187], v178 offset:1024
	ds_read_b128 v[188:191], v178 offset:2048
	ds_read_b128 v[192:195], v178 offset:3072
	ds_read_b128 v[196:199], v178 offset:4096
	ds_read_b128 v[200:203], v178 offset:5120
	ds_read_b128 v[204:207], v178 offset:6144
	global_load_lds_dwordx4 v136, s[36:37]
	s_add_i32 m0, s45, 0xe000
	ds_read_b128 v[208:211], v178 offset:7168
	global_load_lds_dwordx4 v138, s[36:37]
	global_load_dwordx4 v[226:229], v223, s[100:101] nt
	s_add_u32 s84, s84, 1
	s_waitcnt vmcnt(9) lgkmcnt(0)
	s_barrier
	v_mfma_i32_16x16x64_i8 v[124:127], v[140:143], v[180:183], v[124:127]
	v_mfma_i32_16x16x64_i8 v[120:123], v[148:151], v[180:183], v[120:123]
	v_mfma_i32_16x16x64_i8 v[116:119], v[140:143], v[188:191], v[116:119]
	v_mfma_i32_16x16x64_i8 v[112:115], v[148:151], v[188:191], v[112:115]
	v_mfma_i32_16x16x64_i8 v[104:107], v[140:143], v[196:199], v[104:107]
	v_mfma_i32_16x16x64_i8 v[96:99], v[148:151], v[196:199], v[96:99]
	v_mfma_i32_16x16x64_i8 v[88:91], v[140:143], v[204:207], v[88:91]
	v_mfma_i32_16x16x64_i8 v[80:83], v[148:151], v[204:207], v[80:83]
	v_mfma_i32_16x16x64_i8 v[124:127], v[144:147], v[184:187], v[124:127]
	v_mfma_i32_16x16x64_i8 v[120:123], v[152:155], v[184:187], v[120:123]
	v_mfma_i32_16x16x64_i8 v[116:119], v[144:147], v[192:195], v[116:119]
	v_mfma_i32_16x16x64_i8 v[112:115], v[152:155], v[192:195], v[112:115]
	v_mfma_i32_16x16x64_i8 v[104:107], v[144:147], v[200:203], v[104:107]
	v_mfma_i32_16x16x64_i8 v[96:99], v[152:155], v[200:203], v[96:99]
	v_mfma_i32_16x16x64_i8 v[88:91], v[144:147], v[208:211], v[88:91]
	v_mfma_i32_16x16x64_i8 v[80:83], v[152:155], v[208:211], v[80:83]
	v_mfma_i32_16x16x64_i8 v[108:111], v[156:159], v[180:183], v[108:111]
	v_mfma_i32_16x16x64_i8 v[100:103], v[164:167], v[180:183], v[100:103]
	v_mfma_i32_16x16x64_i8 v[92:95], v[156:159], v[188:191], v[92:95]
	v_mfma_i32_16x16x64_i8 v[84:87], v[164:167], v[188:191], v[84:87]
	v_mfma_i32_16x16x64_i8 v[76:79], v[156:159], v[196:199], v[76:79]
	v_mfma_i32_16x16x64_i8 v[72:75], v[164:167], v[196:199], v[72:75]
	v_mfma_i32_16x16x64_i8 v[68:71], v[156:159], v[204:207], v[68:71]
	v_mfma_i32_16x16x64_i8 v[64:67], v[164:167], v[204:207], v[64:67]
	v_mfma_i32_16x16x64_i8 v[108:111], v[160:163], v[184:187], v[108:111]
	v_mfma_i32_16x16x64_i8 v[100:103], v[168:171], v[184:187], v[100:103]
	v_mfma_i32_16x16x64_i8 v[92:95], v[160:163], v[192:195], v[92:95]
	v_mfma_i32_16x16x64_i8 v[84:87], v[168:171], v[192:195], v[84:87]
	v_mfma_i32_16x16x64_i8 v[76:79], v[160:163], v[200:203], v[76:79]
	v_mfma_i32_16x16x64_i8 v[72:75], v[168:171], v[200:203], v[72:75]
	v_mfma_i32_16x16x64_i8 v[68:71], v[160:163], v[208:211], v[68:71]
	v_mfma_i32_16x16x64_i8 v[64:67], v[168:171], v[208:211], v[64:67]
	s_barrier
	s_add_i32 s75, s55, s42
	v_lshl_add_u64 v[172:173], s[38:39], 0, v[130:131]
	s_mov_b32 m0, s75
	ds_read_b128 v[180:183], v178 offset:16384
	ds_read_b128 v[184:187], v178 offset:17408
	ds_read_b128 v[188:191], v178 offset:18432
	ds_read_b128 v[192:195], v178 offset:19456
	ds_read_b128 v[196:199], v178 offset:20480
	global_load_lds_dwordx4 v130, s[38:39]
	s_add_i32 m0, s75, 0x2000
	s_add_u32 s76, s38, 0x80000
	v_lshl_add_u64 v[212:213], s[38:39], 0, v[134:135]
	s_addc_u32 s77, s39, 0
	s_add_i32 s75, s60, s42
	global_load_lds_dwordx4 v134, s[38:39]
	s_mov_b32 m0, s75
	v_lshl_add_u64 v[216:217], s[40:41], 0, v[132:133]
	global_load_lds_dwordx4 v130, s[76:77]
	s_add_i32 m0, s75, 0x2000
	ds_read_b128 v[208:211], v178 offset:23552
	global_load_lds_dwordx4 v134, s[76:77]
	v_lshl_add_u64 v[214:215], s[40:41], 0, v[128:129]
	s_mov_b32 m0, s45
	ds_read_b128 v[204:207], v178 offset:22528
	global_load_lds_dwordx4 v128, s[40:41]
	s_mov_b32 m0, s46
	ds_read_b128 v[200:203], v178 offset:21504
	global_load_lds_dwordx4 v132, s[40:41]
	s_waitcnt vmcnt(9) lgkmcnt(0)
	s_barrier
	v_mfma_i32_16x16x64_i8 v[60:63], v[140:143], v[180:183], v[60:63]
	v_mfma_i32_16x16x64_i8 v[56:59], v[148:151], v[180:183], v[56:59]
	v_mfma_i32_16x16x64_i8 v[52:55], v[140:143], v[188:191], v[52:55]
	v_mfma_i32_16x16x64_i8 v[48:51], v[148:151], v[188:191], v[48:51]
	v_mfma_i32_16x16x64_i8 v[40:43], v[140:143], v[196:199], v[40:43]
	v_mfma_i32_16x16x64_i8 v[32:35], v[148:151], v[196:199], v[32:35]
	v_mfma_i32_16x16x64_i8 v[24:27], v[140:143], v[204:207], v[24:27]
	v_mfma_i32_16x16x64_i8 v[16:19], v[148:151], v[204:207], v[16:19]
	v_mfma_i32_16x16x64_i8 v[60:63], v[144:147], v[184:187], v[60:63]
	v_mfma_i32_16x16x64_i8 v[56:59], v[152:155], v[184:187], v[56:59]
	v_mfma_i32_16x16x64_i8 v[52:55], v[144:147], v[192:195], v[52:55]
	v_mfma_i32_16x16x64_i8 v[48:51], v[152:155], v[192:195], v[48:51]
	v_mfma_i32_16x16x64_i8 v[40:43], v[144:147], v[200:203], v[40:43]
	v_mfma_i32_16x16x64_i8 v[32:35], v[152:155], v[200:203], v[32:35]
	v_mfma_i32_16x16x64_i8 v[24:27], v[144:147], v[208:211], v[24:27]
	v_mfma_i32_16x16x64_i8 v[16:19], v[152:155], v[208:211], v[16:19]
	v_mfma_i32_16x16x64_i8 v[44:47], v[156:159], v[180:183], v[44:47]
	v_mfma_i32_16x16x64_i8 v[36:39], v[164:167], v[180:183], v[36:39]
	v_mfma_i32_16x16x64_i8 v[28:31], v[156:159], v[188:191], v[28:31]
	v_mfma_i32_16x16x64_i8 v[20:23], v[164:167], v[188:191], v[20:23]
	v_mfma_i32_16x16x64_i8 v[12:15], v[156:159], v[196:199], v[12:15]
	v_mfma_i32_16x16x64_i8 v[8:11], v[164:167], v[196:199], v[8:11]
	v_mfma_i32_16x16x64_i8 v[4:7], v[156:159], v[204:207], v[4:7]
	v_mfma_i32_16x16x64_i8 v[0:3], v[164:167], v[204:207], v[0:3]
	v_mfma_i32_16x16x64_i8 v[44:47], v[160:163], v[184:187], v[44:47]
	v_mfma_i32_16x16x64_i8 v[36:39], v[168:171], v[184:187], v[36:39]
	v_mfma_i32_16x16x64_i8 v[28:31], v[160:163], v[192:195], v[28:31]
	v_mfma_i32_16x16x64_i8 v[20:23], v[168:171], v[192:195], v[20:23]
	v_mfma_i32_16x16x64_i8 v[12:15], v[160:163], v[200:203], v[12:15]
	v_mfma_i32_16x16x64_i8 v[8:11], v[168:171], v[200:203], v[8:11]
	v_mfma_i32_16x16x64_i8 v[4:7], v[160:163], v[208:211], v[4:7]
	v_mfma_i32_16x16x64_i8 v[0:3], v[168:171], v[208:211], v[0:3]
	s_barrier
	s_add_i32 s75, 0, 0x18000
	s_add_i32 s76, 0, 0x1c000
	ds_read_b128 v[140:143], v177 offset:32768
	ds_read_b128 v[144:147], v177 offset:33792
	ds_read_b128 v[148:151], v177 offset:34816
	ds_read_b128 v[152:155], v177 offset:35840
	ds_read_b128 v[156:159], v177 offset:49152
	ds_read_b128 v[160:163], v177 offset:50176
	ds_read_b128 v[164:167], v177 offset:51200
	ds_read_b128 v[168:171], v177 offset:52224
	s_add_u32 s40, s40, 0x80000
	s_addc_u32 s41, s41, 0
	s_mov_b32 m0, s47
	ds_read_b128 v[180:183], v178 offset:32768
	ds_read_b128 v[184:187], v178 offset:33792
	ds_read_b128 v[188:191], v178 offset:34816
	ds_read_b128 v[192:195], v178 offset:35840
	ds_read_b128 v[196:199], v178 offset:36864
	ds_read_b128 v[200:203], v178 offset:37888
	ds_read_b128 v[204:207], v178 offset:38912
	global_load_lds_dwordx4 v128, s[40:41]
	s_mov_b32 m0, s48
	ds_read_b128 v[208:211], v178 offset:39936
	global_load_lds_dwordx4 v132, s[40:41]
	s_waitcnt vmcnt(9) lgkmcnt(0)
	s_barrier
	v_mfma_i32_16x16x64_i8 v[124:127], v[140:143], v[180:183], v[124:127]
	v_mfma_i32_16x16x64_i8 v[120:123], v[148:151], v[180:183], v[120:123]
	v_mfma_i32_16x16x64_i8 v[116:119], v[140:143], v[188:191], v[116:119]
	v_mfma_i32_16x16x64_i8 v[112:115], v[148:151], v[188:191], v[112:115]
	v_mfma_i32_16x16x64_i8 v[104:107], v[140:143], v[196:199], v[104:107]
	v_mfma_i32_16x16x64_i8 v[96:99], v[148:151], v[196:199], v[96:99]
	v_mfma_i32_16x16x64_i8 v[88:91], v[140:143], v[204:207], v[88:91]
	v_mfma_i32_16x16x64_i8 v[80:83], v[148:151], v[204:207], v[80:83]
	v_mfma_i32_16x16x64_i8 v[124:127], v[144:147], v[184:187], v[124:127]
	v_mfma_i32_16x16x64_i8 v[120:123], v[152:155], v[184:187], v[120:123]
	v_mfma_i32_16x16x64_i8 v[116:119], v[144:147], v[192:195], v[116:119]
	v_mfma_i32_16x16x64_i8 v[112:115], v[152:155], v[192:195], v[112:115]
	v_mfma_i32_16x16x64_i8 v[104:107], v[144:147], v[200:203], v[104:107]
	v_mfma_i32_16x16x64_i8 v[96:99], v[152:155], v[200:203], v[96:99]
	v_mfma_i32_16x16x64_i8 v[88:91], v[144:147], v[208:211], v[88:91]
	v_mfma_i32_16x16x64_i8 v[80:83], v[152:155], v[208:211], v[80:83]
	v_mfma_i32_16x16x64_i8 v[108:111], v[156:159], v[180:183], v[108:111]
	v_mfma_i32_16x16x64_i8 v[100:103], v[164:167], v[180:183], v[100:103]
	v_mfma_i32_16x16x64_i8 v[92:95], v[156:159], v[188:191], v[92:95]
	v_mfma_i32_16x16x64_i8 v[84:87], v[164:167], v[188:191], v[84:87]
	v_mfma_i32_16x16x64_i8 v[76:79], v[156:159], v[196:199], v[76:79]
	v_mfma_i32_16x16x64_i8 v[72:75], v[164:167], v[196:199], v[72:75]
	v_mfma_i32_16x16x64_i8 v[68:71], v[156:159], v[204:207], v[68:71]
	v_mfma_i32_16x16x64_i8 v[64:67], v[164:167], v[204:207], v[64:67]
	v_mfma_i32_16x16x64_i8 v[108:111], v[160:163], v[184:187], v[108:111]
	v_mfma_i32_16x16x64_i8 v[100:103], v[168:171], v[184:187], v[100:103]
	v_mfma_i32_16x16x64_i8 v[92:95], v[160:163], v[192:195], v[92:95]
	v_mfma_i32_16x16x64_i8 v[84:87], v[168:171], v[192:195], v[84:87]
	v_mfma_i32_16x16x64_i8 v[76:79], v[160:163], v[200:203], v[76:79]
	v_mfma_i32_16x16x64_i8 v[72:75], v[168:171], v[200:203], v[72:75]
	v_mfma_i32_16x16x64_i8 v[68:71], v[160:163], v[208:211], v[68:71]
	v_mfma_i32_16x16x64_i8 v[64:67], v[168:171], v[208:211], v[64:67]
	s_barrier
	s_add_i32 s40, s75, s42
	v_lshl_add_u64 v[172:173], v[172:173], 0, s[20:21]
	s_mov_b32 m0, s40
	ds_read_b128 v[180:183], v178 offset:49152
	ds_read_b128 v[184:187], v178 offset:50176
	ds_read_b128 v[188:191], v178 offset:51200
	ds_read_b128 v[192:195], v178 offset:52224
	global_load_lds_dwordx4 v[172:173], off
	s_add_i32 m0, s40, 0x2000
	s_add_u32 s38, s38, 0x80080
	v_lshl_add_u64 v[172:173], v[212:213], 0, s[20:21]
	s_addc_u32 s39, s39, 0
	s_add_i32 s40, s76, s42
	global_load_lds_dwordx4 v[172:173], off
	s_mov_b32 m0, s40
	ds_read_b128 v[208:211], v178 offset:56320
	global_load_lds_dwordx4 v130, s[38:39]
	s_add_i32 m0, s40, 0x2000
	ds_read_b128 v[204:207], v178 offset:55296
	global_load_lds_dwordx4 v134, s[38:39]
	v_lshl_add_u64 v[172:173], v[214:215], 0, s[20:21]
	s_mov_b32 m0, s51
	ds_read_b128 v[200:203], v178 offset:54272
	global_load_lds_dwordx4 v[172:173], off
	v_lshl_add_u64 v[172:173], v[216:217], 0, s[20:21]
	s_mov_b32 m0, s52
	ds_read_b128 v[196:199], v178 offset:53248
	global_load_lds_dwordx4 v[172:173], off
	s_waitcnt vmcnt(8) lgkmcnt(0)
	s_barrier
	v_mfma_i32_16x16x64_i8 v[60:63], v[140:143], v[180:183], v[60:63]
	v_mfma_i32_16x16x64_i8 v[56:59], v[148:151], v[180:183], v[56:59]
	v_mfma_i32_16x16x64_i8 v[52:55], v[140:143], v[188:191], v[52:55]
	v_fmaak_f32 v226, v226, v220, 0x4b400000
	v_mfma_i32_16x16x64_i8 v[48:51], v[148:151], v[188:191], v[48:51]
	v_mfma_i32_16x16x64_i8 v[40:43], v[140:143], v[196:199], v[40:43]
	v_mfma_i32_16x16x64_i8 v[32:35], v[148:151], v[196:199], v[32:35]
	v_fmaak_f32 v227, v227, v225, 0x4b400000
	v_mfma_i32_16x16x64_i8 v[24:27], v[140:143], v[204:207], v[24:27]
	v_mfma_i32_16x16x64_i8 v[16:19], v[148:151], v[204:207], v[16:19]
	v_mfma_i32_16x16x64_i8 v[60:63], v[144:147], v[184:187], v[60:63]
	v_fmaak_f32 v228, v228, v252, 0x4b400000
	v_mfma_i32_16x16x64_i8 v[56:59], v[152:155], v[184:187], v[56:59]
	v_mfma_i32_16x16x64_i8 v[52:55], v[144:147], v[192:195], v[52:55]
	v_mfma_i32_16x16x64_i8 v[48:51], v[152:155], v[192:195], v[48:51]
	v_fmaak_f32 v229, v229, v253, 0x4b400000
	v_mfma_i32_16x16x64_i8 v[40:43], v[144:147], v[200:203], v[40:43]
	v_mfma_i32_16x16x64_i8 v[32:35], v[152:155], v[200:203], v[32:35]
	v_mfma_i32_16x16x64_i8 v[24:27], v[144:147], v[208:211], v[24:27]
	v_alignbit_b32 v239, v226, v239, 8
	v_mfma_i32_16x16x64_i8 v[16:19], v[152:155], v[208:211], v[16:19]
	v_mfma_i32_16x16x64_i8 v[44:47], v[156:159], v[180:183], v[44:47]
	v_mfma_i32_16x16x64_i8 v[36:39], v[164:167], v[180:183], v[36:39]
	v_alignbit_b32 v243, v227, v243, 8
	v_mfma_i32_16x16x64_i8 v[28:31], v[156:159], v[188:191], v[28:31]
	v_mfma_i32_16x16x64_i8 v[20:23], v[164:167], v[188:191], v[20:23]
	v_mfma_i32_16x16x64_i8 v[12:15], v[156:159], v[196:199], v[12:15]
	v_alignbit_b32 v247, v228, v247, 8
	v_mfma_i32_16x16x64_i8 v[8:11], v[164:167], v[196:199], v[8:11]
	v_mfma_i32_16x16x64_i8 v[4:7], v[156:159], v[204:207], v[4:7]
	v_mfma_i32_16x16x64_i8 v[0:3], v[164:167], v[204:207], v[0:3]
	v_alignbit_b32 v251, v229, v251, 8
	v_mfma_i32_16x16x64_i8 v[44:47], v[160:163], v[184:187], v[44:47]
	v_mfma_i32_16x16x64_i8 v[36:39], v[168:171], v[184:187], v[36:39]
	v_mfma_i32_16x16x64_i8 v[28:31], v[160:163], v[192:195], v[28:31]
	v_add_u32_e32 v223, 0x4000, v223
	v_mfma_i32_16x16x64_i8 v[20:23], v[168:171], v[192:195], v[20:23]
	v_mfma_i32_16x16x64_i8 v[12:15], v[160:163], v[200:203], v[12:15]
	v_mfma_i32_16x16x64_i8 v[8:11], v[168:171], v[200:203], v[8:11]
	v_mfma_i32_16x16x64_i8 v[4:7], v[160:163], v[208:211], v[4:7]
	v_mfma_i32_16x16x64_i8 v[0:3], v[168:171], v[208:211], v[0:3]
	s_barrier
	s_and_b32 s77, s84, 3
	s_cbranch_scc0 .Lq_mv_L

.Lq_st_j:
	s_waitcnt vmcnt(13) lgkmcnt(0)
	s_barrier
	v_mfma_i32_16x16x64_i8 v[124:127], v[140:143], v[180:183], v[124:127]
	v_mfma_i32_16x16x64_i8 v[120:123], v[148:151], v[180:183], v[120:123]
	v_mfma_i32_16x16x64_i8 v[116:119], v[140:143], v[188:191], v[116:119]
	v_mfma_i32_16x16x64_i8 v[112:115], v[148:151], v[188:191], v[112:115]
	v_mfma_i32_16x16x64_i8 v[104:107], v[140:143], v[196:199], v[104:107]
	v_mfma_i32_16x16x64_i8 v[96:99], v[148:151], v[196:199], v[96:99]
	v_mfma_i32_16x16x64_i8 v[88:91], v[140:143], v[204:207], v[88:91]
	v_mfma_i32_16x16x64_i8 v[80:83], v[148:151], v[204:207], v[80:83]
	v_mfma_i32_16x16x64_i8 v[124:127], v[144:147], v[184:187], v[124:127]
	v_mfma_i32_16x16x64_i8 v[120:123], v[152:155], v[184:187], v[120:123]
	v_mfma_i32_16x16x64_i8 v[116:119], v[144:147], v[192:195], v[116:119]
	v_mfma_i32_16x16x64_i8 v[112:115], v[152:155], v[192:195], v[112:115]
	v_mfma_i32_16x16x64_i8 v[104:107], v[144:147], v[200:203], v[104:107]
	v_mfma_i32_16x16x64_i8 v[96:99], v[152:155], v[200:203], v[96:99]
	v_mfma_i32_16x16x64_i8 v[88:91], v[144:147], v[208:211], v[88:91]
	v_mfma_i32_16x16x64_i8 v[80:83], v[152:155], v[208:211], v[80:83]
	v_mfma_i32_16x16x64_i8 v[108:111], v[156:159], v[180:183], v[108:111]
	v_mfma_i32_16x16x64_i8 v[100:103], v[164:167], v[180:183], v[100:103]
	v_mfma_i32_16x16x64_i8 v[92:95], v[156:159], v[188:191], v[92:95]
	v_mfma_i32_16x16x64_i8 v[84:87], v[164:167], v[188:191], v[84:87]
	v_mfma_i32_16x16x64_i8 v[76:79], v[156:159], v[196:199], v[76:79]
	v_mfma_i32_16x16x64_i8 v[72:75], v[164:167], v[196:199], v[72:75]
	v_mfma_i32_16x16x64_i8 v[68:71], v[156:159], v[204:207], v[68:71]
	v_mfma_i32_16x16x64_i8 v[64:67], v[164:167], v[204:207], v[64:67]
	v_mfma_i32_16x16x64_i8 v[108:111], v[160:163], v[184:187], v[108:111]
	v_mfma_i32_16x16x64_i8 v[100:103], v[168:171], v[184:187], v[100:103]
	v_mfma_i32_16x16x64_i8 v[92:95], v[160:163], v[192:195], v[92:95]
	v_mfma_i32_16x16x64_i8 v[84:87], v[168:171], v[192:195], v[84:87]
	v_mfma_i32_16x16x64_i8 v[76:79], v[160:163], v[200:203], v[76:79]
	v_mfma_i32_16x16x64_i8 v[72:75], v[168:171], v[200:203], v[72:75]
	v_mfma_i32_16x16x64_i8 v[68:71], v[160:163], v[208:211], v[68:71]
	v_mfma_i32_16x16x64_i8 v[64:67], v[168:171], v[208:211], v[64:67]
	s_barrier
	s_add_i32 s75, s55, s42
	v_lshl_add_u64 v[172:173], s[38:39], 0, v[130:131]
	s_mov_b32 m0, s75
	ds_read_b128 v[180:183], v178 offset:16384
	ds_read_b128 v[184:187], v178 offset:17408
	ds_read_b128 v[188:191], v178 offset:18432
	ds_read_b128 v[192:195], v178 offset:19456
	ds_read_b128 v[196:199], v178 offset:20480
	global_load_lds_dwordx4 v130, s[38:39]
	s_add_i32 m0, s75, 0x2000
	s_add_u32 s76, s38, 0x80000
	v_lshl_add_u64 v[212:213], s[38:39], 0, v[134:135]
	s_addc_u32 s77, s39, 0
	s_add_i32 s75, s60, s42
	global_load_lds_dwordx4 v134, s[38:39]
	s_mov_b32 m0, s75
	v_lshl_add_u64 v[216:217], s[40:41], 0, v[132:133]
	global_load_lds_dwordx4 v130, s[76:77]
	s_add_i32 m0, s75, 0x2000
	ds_read_b128 v[208:211], v178 offset:23552
	global_load_lds_dwordx4 v134, s[76:77]
	v_lshl_add_u64 v[214:215], s[40:41], 0, v[128:129]
	s_mov_b32 m0, s45
	ds_read_b128 v[204:207], v178 offset:22528
	global_load_lds_dwordx4 v128, s[40:41]
	s_mov_b32 m0, s46
	ds_read_b128 v[200:203], v178 offset:21504
	global_load_lds_dwordx4 v132, s[40:41]
	s_waitcnt vmcnt(13) lgkmcnt(0)
	s_barrier
	v_mfma_i32_16x16x64_i8 v[60:63], v[140:143], v[180:183], v[60:63]
	v_mfma_i32_16x16x64_i8 v[56:59], v[148:151], v[180:183], v[56:59]
	v_mfma_i32_16x16x64_i8 v[52:55], v[140:143], v[188:191], v[52:55]
	v_mfma_i32_16x16x64_i8 v[48:51], v[148:151], v[188:191], v[48:51]
	v_mfma_i32_16x16x64_i8 v[40:43], v[140:143], v[196:199], v[40:43]
	v_mfma_i32_16x16x64_i8 v[32:35], v[148:151], v[196:199], v[32:35]
	v_mfma_i32_16x16x64_i8 v[24:27], v[140:143], v[204:207], v[24:27]
	v_mfma_i32_16x16x64_i8 v[16:19], v[148:151], v[204:207], v[16:19]
	v_mfma_i32_16x16x64_i8 v[60:63], v[144:147], v[184:187], v[60:63]
	v_mfma_i32_16x16x64_i8 v[56:59], v[152:155], v[184:187], v[56:59]
	v_mfma_i32_16x16x64_i8 v[52:55], v[144:147], v[192:195], v[52:55]
	v_mfma_i32_16x16x64_i8 v[48:51], v[152:155], v[192:195], v[48:51]
	v_mfma_i32_16x16x64_i8 v[40:43], v[144:147], v[200:203], v[40:43]
	v_mfma_i32_16x16x64_i8 v[32:35], v[152:155], v[200:203], v[32:35]
	v_mfma_i32_16x16x64_i8 v[24:27], v[144:147], v[208:211], v[24:27]
	v_mfma_i32_16x16x64_i8 v[16:19], v[152:155], v[208:211], v[16:19]
	v_mfma_i32_16x16x64_i8 v[44:47], v[156:159], v[180:183], v[44:47]
	v_mfma_i32_16x16x64_i8 v[36:39], v[164:167], v[180:183], v[36:39]
	v_mfma_i32_16x16x64_i8 v[28:31], v[156:159], v[188:191], v[28:31]
	v_mfma_i32_16x16x64_i8 v[20:23], v[164:167], v[188:191], v[20:23]
	v_mfma_i32_16x16x64_i8 v[12:15], v[156:159], v[196:199], v[12:15]
	v_mfma_i32_16x16x64_i8 v[8:11], v[164:167], v[196:199], v[8:11]
	v_mfma_i32_16x16x64_i8 v[4:7], v[156:159], v[204:207], v[4:7]
	v_mfma_i32_16x16x64_i8 v[0:3], v[164:167], v[204:207], v[0:3]
	v_mfma_i32_16x16x64_i8 v[44:47], v[160:163], v[184:187], v[44:47]
	v_mfma_i32_16x16x64_i8 v[36:39], v[168:171], v[184:187], v[36:39]
	v_mfma_i32_16x16x64_i8 v[28:31], v[160:163], v[192:195], v[28:31]
	v_mfma_i32_16x16x64_i8 v[20:23], v[168:171], v[192:195], v[20:23]
	v_mfma_i32_16x16x64_i8 v[12:15], v[160:163], v[200:203], v[12:15]
	v_mfma_i32_16x16x64_i8 v[8:11], v[168:171], v[200:203], v[8:11]
	v_mfma_i32_16x16x64_i8 v[4:7], v[160:163], v[208:211], v[4:7]
	v_mfma_i32_16x16x64_i8 v[0:3], v[168:171], v[208:211], v[0:3]
	s_barrier
	s_add_i32 s75, 0, 0x18000
	s_add_i32 s76, 0, 0x1c000
	ds_read_b128 v[140:143], v177 offset:32768
	ds_read_b128 v[144:147], v177 offset:33792
	ds_read_b128 v[148:151], v177 offset:34816
	ds_read_b128 v[152:155], v177 offset:35840
	ds_read_b128 v[156:159], v177 offset:49152
	ds_read_b128 v[160:163], v177 offset:50176
	ds_read_b128 v[164:167], v177 offset:51200
	ds_read_b128 v[168:171], v177 offset:52224
	s_add_u32 s40, s40, 0x80000
	s_addc_u32 s41, s41, 0
	s_mov_b32 m0, s47
	ds_read_b128 v[180:183], v178 offset:32768
	ds_read_b128 v[184:187], v178 offset:33792
	ds_read_b128 v[188:191], v178 offset:34816
	ds_read_b128 v[192:195], v178 offset:35840
	ds_read_b128 v[196:199], v178 offset:36864
	ds_read_b128 v[200:203], v178 offset:37888
	ds_read_b128 v[204:207], v178 offset:38912
	global_load_lds_dwordx4 v128, s[40:41]
	s_mov_b32 m0, s48
	ds_read_b128 v[208:211], v178 offset:39936
	global_load_lds_dwordx4 v132, s[40:41]
	s_waitcnt vmcnt(13) lgkmcnt(0)
	s_barrier
	v_mfma_i32_16x16x64_i8 v[124:127], v[140:143], v[180:183], v[124:127]
	v_mfma_i32_16x16x64_i8 v[120:123], v[148:151], v[180:183], v[120:123]
	v_mfma_i32_16x16x64_i8 v[116:119], v[140:143], v[188:191], v[116:119]
	v_mfma_i32_16x16x64_i8 v[112:115], v[148:151], v[188:191], v[112:115]
	v_mfma_i32_16x16x64_i8 v[104:107], v[140:143], v[196:199], v[104:107]
	v_mfma_i32_16x16x64_i8 v[96:99], v[148:151], v[196:199], v[96:99]
	v_mfma_i32_16x16x64_i8 v[88:91], v[140:143], v[204:207], v[88:91]
	v_mfma_i32_16x16x64_i8 v[80:83], v[148:151], v[204:207], v[80:83]
	v_mfma_i32_16x16x64_i8 v[124:127], v[144:147], v[184:187], v[124:127]
	v_mfma_i32_16x16x64_i8 v[120:123], v[152:155], v[184:187], v[120:123]
	v_mfma_i32_16x16x64_i8 v[116:119], v[144:147], v[192:195], v[116:119]
	v_mfma_i32_16x16x64_i8 v[112:115], v[152:155], v[192:195], v[112:115]
	v_mfma_i32_16x16x64_i8 v[104:107], v[144:147], v[200:203], v[104:107]
	v_mfma_i32_16x16x64_i8 v[96:99], v[152:155], v[200:203], v[96:99]
	v_mfma_i32_16x16x64_i8 v[88:91], v[144:147], v[208:211], v[88:91]
	v_mfma_i32_16x16x64_i8 v[80:83], v[152:155], v[208:211], v[80:83]
	v_mfma_i32_16x16x64_i8 v[108:111], v[156:159], v[180:183], v[108:111]
	v_mfma_i32_16x16x64_i8 v[100:103], v[164:167], v[180:183], v[100:103]
	v_mfma_i32_16x16x64_i8 v[92:95], v[156:159], v[188:191], v[92:95]
	v_mfma_i32_16x16x64_i8 v[84:87], v[164:167], v[188:191], v[84:87]
	v_mfma_i32_16x16x64_i8 v[76:79], v[156:159], v[196:199], v[76:79]
	v_mfma_i32_16x16x64_i8 v[72:75], v[164:167], v[196:199], v[72:75]
	v_mfma_i32_16x16x64_i8 v[68:71], v[156:159], v[204:207], v[68:71]
	v_mfma_i32_16x16x64_i8 v[64:67], v[164:167], v[204:207], v[64:67]
	v_mfma_i32_16x16x64_i8 v[108:111], v[160:163], v[184:187], v[108:111]
	v_mfma_i32_16x16x64_i8 v[100:103], v[168:171], v[184:187], v[100:103]
	v_mfma_i32_16x16x64_i8 v[92:95], v[160:163], v[192:195], v[92:95]
	v_mfma_i32_16x16x64_i8 v[84:87], v[168:171], v[192:195], v[84:87]
	v_mfma_i32_16x16x64_i8 v[76:79], v[160:163], v[200:203], v[76:79]
	v_mfma_i32_16x16x64_i8 v[72:75], v[168:171], v[200:203], v[72:75]
	v_mfma_i32_16x16x64_i8 v[68:71], v[160:163], v[208:211], v[68:71]
	v_mfma_i32_16x16x64_i8 v[64:67], v[168:171], v[208:211], v[64:67]
	s_barrier
	s_add_i32 s40, s75, s42
	v_lshl_add_u64 v[172:173], v[172:173], 0, s[20:21]
	s_mov_b32 m0, s40
	ds_read_b128 v[180:183], v178 offset:49152
	ds_read_b128 v[184:187], v178 offset:50176
	ds_read_b128 v[188:191], v178 offset:51200
	ds_read_b128 v[192:195], v178 offset:52224
	global_load_lds_dwordx4 v[172:173], off
	s_add_i32 m0, s40, 0x2000
	s_add_u32 s38, s38, 0x80080
	v_lshl_add_u64 v[172:173], v[212:213], 0, s[20:21]
	s_addc_u32 s39, s39, 0
	s_add_i32 s40, s76, s42
	global_load_lds_dwordx4 v[172:173], off
	s_mov_b32 m0, s40
	ds_read_b128 v[208:211], v178 offset:56320
	global_load_lds_dwordx4 v130, s[38:39]
	s_add_i32 m0, s40, 0x2000
	ds_read_b128 v[204:207], v178 offset:55296
	global_load_lds_dwordx4 v134, s[38:39]
	v_lshl_add_u64 v[172:173], v[214:215], 0, s[20:21]
	s_mov_b32 m0, s51
	ds_read_b128 v[200:203], v178 offset:54272
	global_load_lds_dwordx4 v[172:173], off
	v_lshl_add_u64 v[172:173], v[216:217], 0, s[20:21]
	s_mov_b32 m0, s52
	ds_read_b128 v[196:199], v178 offset:53248
	global_load_lds_dwordx4 v[172:173], off
	s_waitcnt vmcnt(8) lgkmcnt(0)
	s_barrier
	v_mfma_i32_16x16x64_i8 v[60:63], v[140:143], v[180:183], v[60:63]
	v_mfma_i32_16x16x64_i8 v[56:59], v[148:151], v[180:183], v[56:59]
	v_mfma_i32_16x16x64_i8 v[52:55], v[140:143], v[188:191], v[52:55]
	v_fmaak_f32 v226, v226, v220, 0x4b400000
	v_mfma_i32_16x16x64_i8 v[48:51], v[148:151], v[188:191], v[48:51]
	v_mfma_i32_16x16x64_i8 v[40:43], v[140:143], v[196:199], v[40:43]
	v_mfma_i32_16x16x64_i8 v[32:35], v[148:151], v[196:199], v[32:35]
	v_fmaak_f32 v227, v227, v225, 0x4b400000
	v_mfma_i32_16x16x64_i8 v[24:27], v[140:143], v[204:207], v[24:27]
	v_mfma_i32_16x16x64_i8 v[16:19], v[148:151], v[204:207], v[16:19]
	v_mfma_i32_16x16x64_i8 v[60:63], v[144:147], v[184:187], v[60:63]
	v_fmaak_f32 v228, v228, v252, 0x4b400000
	v_mfma_i32_16x16x64_i8 v[56:59], v[152:155], v[184:187], v[56:59]
	v_mfma_i32_16x16x64_i8 v[52:55], v[144:147], v[192:195], v[52:55]
	v_mfma_i32_16x16x64_i8 v[48:51], v[152:155], v[192:195], v[48:51]
	v_fmaak_f32 v229, v229, v253, 0x4b400000
	v_mfma_i32_16x16x64_i8 v[40:43], v[144:147], v[200:203], v[40:43]
	v_mfma_i32_16x16x64_i8 v[32:35], v[152:155], v[200:203], v[32:35]
	v_mfma_i32_16x16x64_i8 v[24:27], v[144:147], v[208:211], v[24:27]
	v_alignbit_b32 v239, v226, v239, 8
	v_mfma_i32_16x16x64_i8 v[16:19], v[152:155], v[208:211], v[16:19]
	v_mfma_i32_16x16x64_i8 v[44:47], v[156:159], v[180:183], v[44:47]
	v_mfma_i32_16x16x64_i8 v[36:39], v[164:167], v[180:183], v[36:39]
	v_alignbit_b32 v243, v227, v243, 8
	v_mfma_i32_16x16x64_i8 v[28:31], v[156:159], v[188:191], v[28:31]
	v_mfma_i32_16x16x64_i8 v[20:23], v[164:167], v[188:191], v[20:23]
	v_mfma_i32_16x16x64_i8 v[12:15], v[156:159], v[196:199], v[12:15]
	v_alignbit_b32 v247, v228, v247, 8
	v_mfma_i32_16x16x64_i8 v[8:11], v[164:167], v[196:199], v[8:11]
	v_mfma_i32_16x16x64_i8 v[4:7], v[156:159], v[204:207], v[4:7]
	v_mfma_i32_16x16x64_i8 v[0:3], v[164:167], v[204:207], v[0:3]
	v_alignbit_b32 v251, v229, v251, 8
	v_mfma_i32_16x16x64_i8 v[44:47], v[160:163], v[184:187], v[44:47]
	v_mfma_i32_16x16x64_i8 v[36:39], v[168:171], v[184:187], v[36:39]
	v_mfma_i32_16x16x64_i8 v[28:31], v[160:163], v[192:195], v[28:31]
	v_add_u32_e32 v223, 0x4000, v223
	v_mfma_i32_16x16x64_i8 v[20:23], v[168:171], v[192:195], v[20:23]
	v_mfma_i32_16x16x64_i8 v[12:15], v[160:163], v[200:203], v[12:15]
	v_mfma_i32_16x16x64_i8 v[8:11], v[168:171], v[200:203], v[8:11]
	v_mfma_i32_16x16x64_i8 v[4:7], v[160:163], v[208:211], v[4:7]
	v_mfma_i32_16x16x64_i8 v[0:3], v[168:171], v[208:211], v[0:3]
	s_barrier
	s_cmp_eq_u32 s32, 0
	s_cbranch_scc1 .Lq_mvx_ST
	s_and_b32 s77, s84, 3
	s_cbranch_scc0 .Lq_mv_ST

.LBB0_1474:
	s_add_i32 s75, s48, 2
	s_add_u32 s46, s44, 0x100
	s_addc_u32 s47, s45, 0
	s_cmp_eq_u32 s72, s48
	s_cselect_b32 s51, s41, s47
	s_cselect_b32 s50, s40, s46
	ds_read_b128 v[140:143], v184
	ds_read_b128 v[144:147], v184 offset:1024
	ds_read_b128 v[148:151], v184 offset:2048
	ds_read_b128 v[152:155], v184 offset:3072
	ds_read_b128 v[156:159], v184 offset:16384
	ds_read_b128 v[160:163], v184 offset:17408
	ds_read_b128 v[164:167], v184 offset:18432
	ds_read_b128 v[168:171], v184 offset:19456
	s_cselect_b32 s48, s42, s73
	s_cselect_b32 s49, s43, s74
	s_add_i32 m0, s54, 0xc000
	ds_read_b128 v[172:175], v186
	ds_read_b128 v[176:179], v186 offset:1024
	ds_read_b128 v[188:191], v186 offset:2048
	ds_read_b128 v[192:195], v186 offset:3072
	ds_read_b128 v[196:199], v186 offset:4096
	ds_read_b128 v[200:203], v186 offset:5120
	ds_read_b128 v[204:207], v186 offset:6144
	global_load_lds_dwordx4 v136, s[44:45]
	s_add_i32 m0, s54, 0xe000
	ds_read_b128 v[208:211], v186 offset:7168
	global_load_lds_dwordx4 v138, s[44:45]
	s_waitcnt vmcnt(8) lgkmcnt(0)
	s_barrier
	v_mfma_i32_16x16x64_i8 v[124:127], v[140:143], v[172:175], v[124:127]
	v_mfma_i32_16x16x64_i8 v[120:123], v[148:151], v[172:175], v[120:123]
	v_mfma_i32_16x16x64_i8 v[116:119], v[140:143], v[188:191], v[116:119]
	v_mfma_i32_16x16x64_i8 v[112:115], v[148:151], v[188:191], v[112:115]
	v_mfma_i32_16x16x64_i8 v[104:107], v[140:143], v[196:199], v[104:107]
	v_mfma_i32_16x16x64_i8 v[96:99], v[148:151], v[196:199], v[96:99]
	v_mfma_i32_16x16x64_i8 v[88:91], v[140:143], v[204:207], v[88:91]
	v_mfma_i32_16x16x64_i8 v[80:83], v[148:151], v[204:207], v[80:83]
	v_mfma_i32_16x16x64_i8 v[124:127], v[144:147], v[176:179], v[124:127]
	v_mfma_i32_16x16x64_i8 v[120:123], v[152:155], v[176:179], v[120:123]
	v_mfma_i32_16x16x64_i8 v[116:119], v[144:147], v[192:195], v[116:119]
	v_mfma_i32_16x16x64_i8 v[112:115], v[152:155], v[192:195], v[112:115]
	v_mfma_i32_16x16x64_i8 v[104:107], v[144:147], v[200:203], v[104:107]
	v_mfma_i32_16x16x64_i8 v[96:99], v[152:155], v[200:203], v[96:99]
	v_mfma_i32_16x16x64_i8 v[88:91], v[144:147], v[208:211], v[88:91]
	v_mfma_i32_16x16x64_i8 v[80:83], v[152:155], v[208:211], v[80:83]
	v_mfma_i32_16x16x64_i8 v[108:111], v[156:159], v[172:175], v[108:111]
	v_mfma_i32_16x16x64_i8 v[100:103], v[164:167], v[172:175], v[100:103]
	v_mfma_i32_16x16x64_i8 v[92:95], v[156:159], v[188:191], v[92:95]
	v_mfma_i32_16x16x64_i8 v[84:87], v[164:167], v[188:191], v[84:87]
	v_mfma_i32_16x16x64_i8 v[76:79], v[156:159], v[196:199], v[76:79]
	v_mfma_i32_16x16x64_i8 v[72:75], v[164:167], v[196:199], v[72:75]
	v_mfma_i32_16x16x64_i8 v[68:71], v[156:159], v[204:207], v[68:71]
	v_mfma_i32_16x16x64_i8 v[64:67], v[164:167], v[204:207], v[64:67]
	v_mfma_i32_16x16x64_i8 v[108:111], v[160:163], v[176:179], v[108:111]
	v_mfma_i32_16x16x64_i8 v[100:103], v[168:171], v[176:179], v[100:103]
	v_mfma_i32_16x16x64_i8 v[92:95], v[160:163], v[192:195], v[92:95]
	v_mfma_i32_16x16x64_i8 v[84:87], v[168:171], v[192:195], v[84:87]
	v_mfma_i32_16x16x64_i8 v[76:79], v[160:163], v[200:203], v[76:79]
	v_mfma_i32_16x16x64_i8 v[72:75], v[168:171], v[200:203], v[72:75]
	v_mfma_i32_16x16x64_i8 v[68:71], v[160:163], v[208:211], v[68:71]
	v_mfma_i32_16x16x64_i8 v[64:67], v[168:171], v[208:211], v[64:67]
	s_barrier
	s_add_i32 s44, s66, s53
	s_mov_b32 m0, s44
	ds_read_b128 v[172:175], v186 offset:16384
	ds_read_b128 v[176:179], v186 offset:17408
	ds_read_b128 v[188:191], v186 offset:18432
	ds_read_b128 v[192:195], v186 offset:19456
	global_load_lds_dwordx4 v130, s[48:49]
	s_add_i32 m0, s44, 0x2000
	s_add_u32 s44, s48, 0x158000
	s_addc_u32 s45, s49, 0
	s_add_i32 s76, s67, s53
	global_load_lds_dwordx4 v134, s[48:49]
	s_mov_b32 m0, s76
	ds_read_b128 v[208:211], v186 offset:23552
	global_load_lds_dwordx4 v130, s[44:45]
	s_add_i32 m0, s76, 0x2000
	ds_read_b128 v[204:207], v186 offset:22528
	global_load_lds_dwordx4 v134, s[44:45]
	s_mov_b32 m0, s54
	ds_read_b128 v[200:203], v186 offset:21504
	global_load_lds_dwordx4 v128, s[50:51]
	s_mov_b32 m0, s55
	ds_read_b128 v[196:199], v186 offset:20480
	global_load_lds_dwordx4 v132, s[50:51]
	s_waitcnt vmcnt(8) lgkmcnt(0)
	s_barrier
	v_mfma_i32_16x16x64_i8 v[60:63], v[140:143], v[172:175], v[60:63]
	v_mfma_i32_16x16x64_i8 v[56:59], v[148:151], v[172:175], v[56:59]
	v_mfma_i32_16x16x64_i8 v[52:55], v[140:143], v[188:191], v[52:55]
	v_mfma_i32_16x16x64_i8 v[48:51], v[148:151], v[188:191], v[48:51]
	v_mfma_i32_16x16x64_i8 v[40:43], v[140:143], v[196:199], v[40:43]
	v_mfma_i32_16x16x64_i8 v[32:35], v[148:151], v[196:199], v[32:35]
	v_mfma_i32_16x16x64_i8 v[24:27], v[140:143], v[204:207], v[24:27]
	v_mfma_i32_16x16x64_i8 v[16:19], v[148:151], v[204:207], v[16:19]
	v_mfma_i32_16x16x64_i8 v[60:63], v[144:147], v[176:179], v[60:63]
	v_mfma_i32_16x16x64_i8 v[56:59], v[152:155], v[176:179], v[56:59]
	v_mfma_i32_16x16x64_i8 v[52:55], v[144:147], v[192:195], v[52:55]
	v_mfma_i32_16x16x64_i8 v[48:51], v[152:155], v[192:195], v[48:51]
	v_mfma_i32_16x16x64_i8 v[40:43], v[144:147], v[200:203], v[40:43]
	v_mfma_i32_16x16x64_i8 v[32:35], v[152:155], v[200:203], v[32:35]
	v_mfma_i32_16x16x64_i8 v[24:27], v[144:147], v[208:211], v[24:27]
	v_mfma_i32_16x16x64_i8 v[16:19], v[152:155], v[208:211], v[16:19]
	v_mfma_i32_16x16x64_i8 v[44:47], v[156:159], v[172:175], v[44:47]
	v_mfma_i32_16x16x64_i8 v[36:39], v[164:167], v[172:175], v[36:39]
	v_mfma_i32_16x16x64_i8 v[28:31], v[156:159], v[188:191], v[28:31]
	v_mfma_i32_16x16x64_i8 v[20:23], v[164:167], v[188:191], v[20:23]
	v_mfma_i32_16x16x64_i8 v[12:15], v[156:159], v[196:199], v[12:15]
	v_mfma_i32_16x16x64_i8 v[8:11], v[164:167], v[196:199], v[8:11]
	v_mfma_i32_16x16x64_i8 v[4:7], v[156:159], v[204:207], v[4:7]
	v_mfma_i32_16x16x64_i8 v[0:3], v[164:167], v[204:207], v[0:3]
	v_mfma_i32_16x16x64_i8 v[44:47], v[160:163], v[176:179], v[44:47]
	v_mfma_i32_16x16x64_i8 v[36:39], v[168:171], v[176:179], v[36:39]
	v_mfma_i32_16x16x64_i8 v[28:31], v[160:163], v[192:195], v[28:31]
	v_mfma_i32_16x16x64_i8 v[20:23], v[168:171], v[192:195], v[20:23]
	v_mfma_i32_16x16x64_i8 v[12:15], v[160:163], v[200:203], v[12:15]
	v_mfma_i32_16x16x64_i8 v[8:11], v[168:171], v[200:203], v[8:11]
	v_mfma_i32_16x16x64_i8 v[4:7], v[160:163], v[208:211], v[4:7]
	v_mfma_i32_16x16x64_i8 v[0:3], v[168:171], v[208:211], v[0:3]
	s_barrier
	s_add_i32 s76, 0, 0x18000
	s_add_i32 s77, 0, 0x1c000
	ds_read_b128 v[140:143], v184 offset:32768
	ds_read_b128 v[144:147], v184 offset:33792
	ds_read_b128 v[148:151], v184 offset:34816
	ds_read_b128 v[152:155], v184 offset:35840
	ds_read_b128 v[156:159], v184 offset:49152
	ds_read_b128 v[160:163], v184 offset:50176
	ds_read_b128 v[164:167], v184 offset:51200
	ds_read_b128 v[168:171], v184 offset:52224
	s_add_u32 s44, s50, 0x158000
	s_addc_u32 s45, s51, 0
	s_mov_b32 m0, s60
	ds_read_b128 v[172:175], v186 offset:32768
	ds_read_b128 v[176:179], v186 offset:33792
	ds_read_b128 v[188:191], v186 offset:34816
	ds_read_b128 v[192:195], v186 offset:35840
	ds_read_b128 v[196:199], v186 offset:36864
	ds_read_b128 v[200:203], v186 offset:37888
	ds_read_b128 v[204:207], v186 offset:38912
	global_load_lds_dwordx4 v128, s[44:45]
	s_mov_b32 m0, s61
	ds_read_b128 v[208:211], v186 offset:39936
	global_load_lds_dwordx4 v132, s[44:45]
	s_waitcnt vmcnt(8) lgkmcnt(0)
	s_barrier
	v_mfma_i32_16x16x64_i8 v[124:127], v[140:143], v[172:175], v[124:127]
	v_mfma_i32_16x16x64_i8 v[120:123], v[148:151], v[172:175], v[120:123]
	v_mfma_i32_16x16x64_i8 v[116:119], v[140:143], v[188:191], v[116:119]
	v_mfma_i32_16x16x64_i8 v[112:115], v[148:151], v[188:191], v[112:115]
	v_mfma_i32_16x16x64_i8 v[104:107], v[140:143], v[196:199], v[104:107]
	v_mfma_i32_16x16x64_i8 v[96:99], v[148:151], v[196:199], v[96:99]
	v_mfma_i32_16x16x64_i8 v[88:91], v[140:143], v[204:207], v[88:91]
	v_mfma_i32_16x16x64_i8 v[80:83], v[148:151], v[204:207], v[80:83]
	v_mfma_i32_16x16x64_i8 v[124:127], v[144:147], v[176:179], v[124:127]
	v_mfma_i32_16x16x64_i8 v[120:123], v[152:155], v[176:179], v[120:123]
	v_mfma_i32_16x16x64_i8 v[116:119], v[144:147], v[192:195], v[116:119]
	v_mfma_i32_16x16x64_i8 v[112:115], v[152:155], v[192:195], v[112:115]
	v_mfma_i32_16x16x64_i8 v[104:107], v[144:147], v[200:203], v[104:107]
	v_mfma_i32_16x16x64_i8 v[96:99], v[152:155], v[200:203], v[96:99]
	v_mfma_i32_16x16x64_i8 v[88:91], v[144:147], v[208:211], v[88:91]
	v_mfma_i32_16x16x64_i8 v[80:83], v[152:155], v[208:211], v[80:83]
	v_mfma_i32_16x16x64_i8 v[108:111], v[156:159], v[172:175], v[108:111]
	v_mfma_i32_16x16x64_i8 v[100:103], v[164:167], v[172:175], v[100:103]
	v_mfma_i32_16x16x64_i8 v[92:95], v[156:159], v[188:191], v[92:95]
	v_mfma_i32_16x16x64_i8 v[84:87], v[164:167], v[188:191], v[84:87]
	v_mfma_i32_16x16x64_i8 v[76:79], v[156:159], v[196:199], v[76:79]
	v_mfma_i32_16x16x64_i8 v[72:75], v[164:167], v[196:199], v[72:75]
	v_mfma_i32_16x16x64_i8 v[68:71], v[156:159], v[204:207], v[68:71]
	v_mfma_i32_16x16x64_i8 v[64:67], v[164:167], v[204:207], v[64:67]
	v_mfma_i32_16x16x64_i8 v[108:111], v[160:163], v[176:179], v[108:111]
	v_mfma_i32_16x16x64_i8 v[100:103], v[168:171], v[176:179], v[100:103]
	v_mfma_i32_16x16x64_i8 v[92:95], v[160:163], v[192:195], v[92:95]
	v_mfma_i32_16x16x64_i8 v[84:87], v[168:171], v[192:195], v[84:87]
	v_mfma_i32_16x16x64_i8 v[76:79], v[160:163], v[200:203], v[76:79]
	v_mfma_i32_16x16x64_i8 v[72:75], v[168:171], v[200:203], v[72:75]
	v_mfma_i32_16x16x64_i8 v[68:71], v[160:163], v[208:211], v[68:71]
	v_mfma_i32_16x16x64_i8 v[64:67], v[168:171], v[208:211], v[64:67]
	s_barrier
	s_add_u32 s98, s48, s18
	s_addc_u32 s99, s49, s19
	s_add_u32 s100, s50, s18
	s_addc_u32 s101, s51, s19
	s_add_i32 s44, s76, s53
	s_mov_b32 m0, s44
	ds_read_b128 v[172:175], v186 offset:49152
	ds_read_b128 v[176:179], v186 offset:50176
	ds_read_b128 v[188:191], v186 offset:51200
	ds_read_b128 v[192:195], v186 offset:52224
	global_load_lds_dwordx4 v130, s[98:99]
	s_add_i32 m0, s44, 0x2000
	s_add_u32 s44, s48, 0x158080
	s_addc_u32 s45, s49, 0
	s_add_i32 s48, s77, s53
	global_load_lds_dwordx4 v134, s[98:99]
	s_mov_b32 m0, s48
	ds_read_b128 v[208:211], v186 offset:56320
	global_load_lds_dwordx4 v130, s[44:45]
	s_add_i32 m0, s48, 0x2000
	ds_read_b128 v[204:207], v186 offset:55296
	global_load_lds_dwordx4 v134, s[44:45]
	s_mov_b32 m0, s64
	ds_read_b128 v[200:203], v186 offset:54272
	global_load_lds_dwordx4 v128, s[100:101]
	s_mov_b32 m0, s65
	ds_read_b128 v[196:199], v186 offset:53248
	global_load_lds_dwordx4 v132, s[100:101]
	s_waitcnt vmcnt(8) lgkmcnt(0)
	s_barrier
	v_mfma_i32_16x16x64_i8 v[60:63], v[140:143], v[172:175], v[60:63]
	v_mfma_i32_16x16x64_i8 v[56:59], v[148:151], v[172:175], v[56:59]
	v_mfma_i32_16x16x64_i8 v[52:55], v[140:143], v[188:191], v[52:55]
	v_mfma_i32_16x16x64_i8 v[48:51], v[148:151], v[188:191], v[48:51]
	v_mfma_i32_16x16x64_i8 v[40:43], v[140:143], v[196:199], v[40:43]
	v_mfma_i32_16x16x64_i8 v[32:35], v[148:151], v[196:199], v[32:35]
	v_mfma_i32_16x16x64_i8 v[24:27], v[140:143], v[204:207], v[24:27]
	v_mfma_i32_16x16x64_i8 v[16:19], v[148:151], v[204:207], v[16:19]
	v_mfma_i32_16x16x64_i8 v[60:63], v[144:147], v[176:179], v[60:63]
	v_mfma_i32_16x16x64_i8 v[56:59], v[152:155], v[176:179], v[56:59]
	v_mfma_i32_16x16x64_i8 v[52:55], v[144:147], v[192:195], v[52:55]
	v_mfma_i32_16x16x64_i8 v[48:51], v[152:155], v[192:195], v[48:51]
	v_mfma_i32_16x16x64_i8 v[40:43], v[144:147], v[200:203], v[40:43]
	v_mfma_i32_16x16x64_i8 v[32:35], v[152:155], v[200:203], v[32:35]
	v_mfma_i32_16x16x64_i8 v[24:27], v[144:147], v[208:211], v[24:27]
	v_mfma_i32_16x16x64_i8 v[16:19], v[152:155], v[208:211], v[16:19]
	v_mfma_i32_16x16x64_i8 v[44:47], v[156:159], v[172:175], v[44:47]
	v_mfma_i32_16x16x64_i8 v[36:39], v[164:167], v[172:175], v[36:39]
	v_mfma_i32_16x16x64_i8 v[28:31], v[156:159], v[188:191], v[28:31]
	v_mfma_i32_16x16x64_i8 v[20:23], v[164:167], v[188:191], v[20:23]
	v_mfma_i32_16x16x64_i8 v[12:15], v[156:159], v[196:199], v[12:15]
	v_mfma_i32_16x16x64_i8 v[8:11], v[164:167], v[196:199], v[8:11]
	v_mfma_i32_16x16x64_i8 v[4:7], v[156:159], v[204:207], v[4:7]
	v_mfma_i32_16x16x64_i8 v[0:3], v[164:167], v[204:207], v[0:3]
	v_mfma_i32_16x16x64_i8 v[44:47], v[160:163], v[176:179], v[44:47]
	v_mfma_i32_16x16x64_i8 v[36:39], v[168:171], v[176:179], v[36:39]
	v_mfma_i32_16x16x64_i8 v[28:31], v[160:163], v[192:195], v[28:31]
	v_mfma_i32_16x16x64_i8 v[20:23], v[168:171], v[192:195], v[20:23]
	v_mfma_i32_16x16x64_i8 v[12:15], v[160:163], v[200:203], v[12:15]
	v_mfma_i32_16x16x64_i8 v[8:11], v[168:171], v[200:203], v[8:11]
	v_mfma_i32_16x16x64_i8 v[4:7], v[160:163], v[208:211], v[4:7]
	v_mfma_i32_16x16x64_i8 v[0:3], v[168:171], v[208:211], v[0:3]
	s_barrier
	s_add_u32 s73, s73, 0x100
	s_addc_u32 s74, s74, 0
	s_cmp_ge_i32 s75, s71
	s_mov_b64 s[44:45], s[46:47]
	s_mov_b32 s48, s75
	s_cbranch_scc0 .LBB0_1474
	v_cvt_f32_i32_e32 v140, v124
	v_cvt_f32_i32_e32 v141, v125
	v_cvt_f32_i32_e32 v124, v126
	v_cvt_f32_i32_e32 v125, v127
	v_cvt_f32_i32_e32 v142, v120
	v_cvt_f32_i32_e32 v143, v121
	v_cvt_f32_i32_e32 v126, v122
	v_cvt_f32_i32_e32 v127, v123
	v_cvt_f32_i32_e32 v146, v108
	v_cvt_f32_i32_e32 v147, v109
	v_cvt_f32_i32_e32 v120, v110
	v_cvt_f32_i32_e32 v121, v111
	v_cvt_f32_i32_e32 v148, v100
	v_cvt_f32_i32_e32 v149, v101
	v_cvt_f32_i32_e32 v122, v102
	v_cvt_f32_i32_e32 v123, v103
	v_cvt_f32_i32_e32 v144, v116
	v_cvt_f32_i32_e32 v145, v117
	v_cvt_f32_i32_e32 v116, v118
	v_cvt_f32_i32_e32 v117, v119
	v_cvt_f32_i32_e32 v118, v112
	v_cvt_f32_i32_e32 v119, v113
	v_cvt_f32_i32_e32 v112, v114
	v_cvt_f32_i32_e32 v113, v115
	v_cvt_f32_i32_e32 v152, v92
	v_cvt_f32_i32_e32 v153, v93
	v_cvt_f32_i32_e32 v100, v94
	v_cvt_f32_i32_e32 v101, v95
	v_cvt_f32_i32_e32 v156, v84
	v_cvt_f32_i32_e32 v157, v85
	v_cvt_f32_i32_e32 v102, v86
	v_cvt_f32_i32_e32 v103, v87
	v_cvt_f32_i32_e32 v114, v104
	v_cvt_f32_i32_e32 v115, v105
	v_cvt_f32_i32_e32 v86, v106
	v_cvt_f32_i32_e32 v87, v107
	v_cvt_f32_i32_e32 v150, v96
	v_cvt_f32_i32_e32 v151, v97
	v_cvt_f32_i32_e32 v92, v98
	v_cvt_f32_i32_e32 v93, v99
	v_cvt_f32_i32_e32 v160, v76
	v_cvt_f32_i32_e32 v161, v77
	v_cvt_f32_i32_e32 v84, v78
	v_cvt_f32_i32_e32 v85, v79
	v_cvt_f32_i32_e32 v162, v72
	v_cvt_f32_i32_e32 v163, v73
	v_cvt_f32_i32_e32 v94, v74
	v_cvt_f32_i32_e32 v95, v75
	v_cvt_f32_i32_e32 v154, v88
	v_cvt_f32_i32_e32 v155, v89
	v_cvt_f32_i32_e32 v78, v90
	v_cvt_f32_i32_e32 v79, v91
	v_cvt_f32_i32_e32 v158, v80
	v_cvt_f32_i32_e32 v159, v81
	v_cvt_f32_i32_e32 v80, v82
	v_cvt_f32_i32_e32 v81, v83
	v_cvt_f32_i32_e32 v164, v68
	v_cvt_f32_i32_e32 v165, v69
	v_cvt_f32_i32_e32 v76, v70
	v_cvt_f32_i32_e32 v77, v71
	v_cvt_f32_i32_e32 v166, v64
	v_cvt_f32_i32_e32 v167, v65
	v_cvt_f32_i32_e32 v82, v66
	v_cvt_f32_i32_e32 v83, v67
	v_cvt_f32_i32_e32 v70, v60
	v_cvt_f32_i32_e32 v71, v61
	v_cvt_f32_i32_e32 v74, v62
	v_cvt_f32_i32_e32 v75, v63
	v_cvt_f32_i32_e32 v68, v56
	v_cvt_f32_i32_e32 v69, v57
	v_cvt_f32_i32_e32 v72, v58
	v_cvt_f32_i32_e32 v73, v59
	v_cvt_f32_i32_e32 v62, v44
	v_cvt_f32_i32_e32 v63, v45
	v_cvt_f32_i32_e32 v66, v46
	v_cvt_f32_i32_e32 v67, v47
	v_cvt_f32_i32_e32 v60, v36
	v_cvt_f32_i32_e32 v61, v37
	v_cvt_f32_i32_e32 v64, v38
	v_cvt_f32_i32_e32 v65, v39
	v_cvt_f32_i32_e32 v56, v52
	v_cvt_f32_i32_e32 v57, v53
	v_cvt_f32_i32_e32 v58, v54
	v_cvt_f32_i32_e32 v59, v55
	v_cvt_f32_i32_e32 v52, v48
	v_cvt_f32_i32_e32 v53, v49
	v_cvt_f32_i32_e32 v54, v50
	v_cvt_f32_i32_e32 v55, v51
	v_cvt_f32_i32_e32 v46, v28
	v_cvt_f32_i32_e32 v47, v29
	v_cvt_f32_i32_e32 v50, v30
	v_cvt_f32_i32_e32 v51, v31
	v_cvt_f32_i32_e32 v44, v20
	v_cvt_f32_i32_e32 v45, v21
	v_cvt_f32_i32_e32 v48, v22
	v_cvt_f32_i32_e32 v49, v23
	v_cvt_f32_i32_e32 v38, v40
	v_cvt_f32_i32_e32 v39, v41
	v_cvt_f32_i32_e32 v42, v42
	v_cvt_f32_i32_e32 v43, v43
	v_cvt_f32_i32_e32 v36, v32
	v_cvt_f32_i32_e32 v37, v33
	v_cvt_f32_i32_e32 v40, v34
	v_cvt_f32_i32_e32 v41, v35
	v_cvt_f32_i32_e32 v30, v12
	v_cvt_f32_i32_e32 v31, v13
	v_cvt_f32_i32_e32 v34, v14
	v_cvt_f32_i32_e32 v35, v15
	v_cvt_f32_i32_e32 v28, v8
	v_cvt_f32_i32_e32 v29, v9
	v_cvt_f32_i32_e32 v32, v10
	v_cvt_f32_i32_e32 v33, v11
	v_cvt_f32_i32_e32 v22, v24
	v_cvt_f32_i32_e32 v23, v25
	v_cvt_f32_i32_e32 v26, v26
	v_cvt_f32_i32_e32 v27, v27
	v_cvt_f32_i32_e32 v20, v16
	v_cvt_f32_i32_e32 v21, v17
	v_cvt_f32_i32_e32 v24, v18
	v_cvt_f32_i32_e32 v25, v19
	v_cvt_f32_i32_e32 v14, v4
	v_cvt_f32_i32_e32 v15, v5
	v_cvt_f32_i32_e32 v18, v6
	v_cvt_f32_i32_e32 v19, v7
	v_cvt_f32_i32_e32 v12, v0
	v_cvt_f32_i32_e32 v13, v1
	v_cvt_f32_i32_e32 v16, v2
	v_cvt_f32_i32_e32 v17, v3
	s_and_b64 vcc, exec, s[20:21]
	s_cbranch_vccz .LBB0_1477
